# baseline (speedup 1.0000x reference)
.LBB0_367:
	v_lshrrev_b32_e32 v18, 1, v8
	v_and_b32_e32 v18, 24, v18
	v_readlane_b32 s18, v254, 18
	v_and_b32_e32 v9, 15, v8
	v_lshlrev_b32_e32 v19, 1, v18
	v_lshlrev_b32_e32 v8, 2, v8
	s_lshl_b32 s1, s1, 5
	v_readlane_b32 s19, v254, 19
	v_lshl_or_b32 v154, s6, 6, v9
	v_lshl_or_b32 v9, v9, 6, v19
	s_lshl_b32 s3, s6, 13
	v_and_b32_e32 v8, 32, v8
	s_and_b32 s1, s1, 0x60
	v_lshl_add_u64 v[10:11], s[18:19], 0, v[0:1]
	v_mov_b32_e32 v131, v1
	v_readlane_b32 s16, v254, 14
	v_bitop3_b32 v19, v9, s3, v8 bitop3:0xde
	s_lshl_b32 s3, s1, 7
	v_lshl_add_u64 v[12:13], s[18:19], 0, v[130:131]
	v_mov_b32_e32 v135, v1
	v_readlane_b32 s17, v254, 15
	v_bitop3_b32 v155, v9, s3, v8 bitop3:0xde
	s_add_i32 m0, s22, 0x18000
	v_lshl_add_u64 v[8:9], v[10:11], 0, s[52:53]
	v_lshl_add_u64 v[14:15], s[16:17], 0, v[134:135]
	v_mov_b32_e32 v133, v1
	s_waitcnt vmcnt(2)
	s_barrier
	global_load_lds_dwordx4 v[8:9], off
	v_lshl_add_u64 v[8:9], v[12:13], 0, s[52:53]
	s_add_i32 m0, s22, 0x1a000
	s_add_i32 s26, s22, 0x8000
	v_lshl_add_u64 v[16:17], s[16:17], 0, v[132:133]
	global_load_lds_dwordx4 v[8:9], off
	v_lshl_add_u64 v[8:9], v[14:15], 0, s[52:53]
	s_mov_b32 m0, s26
	s_add_i32 s27, s22, 0xa000
	v_readlane_b32 s6, v254, 20
	global_load_lds_dwordx4 v[8:9], off
	v_lshl_add_u64 v[8:9], v[16:17], 0, s[52:53]
	s_mov_b32 m0, s27
	v_readlane_b32 s7, v254, 21
	global_load_lds_dwordx4 v[8:9], off
	s_add_i32 m0, s22, 0x1c000
	s_nop 0
	global_load_lds_dwordx4 v0, s[6:7]
	s_add_i32 m0, s22, 0x1e000
	s_cmpk_lt_u32 s0, 0x100
	global_load_lds_dwordx4 v130, s[6:7]
	v_lshlrev_b32_e32 v8, 15, v6
	v_and_b32_e32 v8, 0xffff0000, v8
	v_lshl_add_u32 v5, v5, 12, v8
	v_and_b32_e32 v6, 1, v6
	v_lshl_or_b32 v5, v6, 6, v5
	v_lshl_add_u32 v136, v7, 1, v5
	v_lshlrev_b32_e32 v5, 15, v2
	v_and_b32_e32 v5, 0xffff0000, v5
	s_waitcnt vmcnt(6)
	v_lshl_add_u32 v3, v3, 12, v5
	v_and_b32_e32 v2, 1, v2
	v_or_b32_e32 v156, s1, v18
	v_lshl_or_b32 v2, v2, 6, v3
	v_readlane_b32 s0, v254, 9
	s_cselect_b64 s[6:7], -1, 0
	v_mov_b32_e32 v137, v1
	v_lshl_add_u32 v138, v4, 1, v2
	v_mov_b32_e32 v139, v1
	s_mov_b32 s28, 0
	v_add_u32_e32 v157, 0, v19
	v_readlane_b32 s30, v254, 8
	s_mov_b32 s29, s0
	s_barrier
	v_readlane_b32 s1, v254, 10
	s_branch .LBB0_370

.LBB0_377:
	s_add_u32 s3, s16, 0xfff80080
	s_addc_u32 s18, s17, -1
	s_add_i32 s42, 0, 0x10000
	s_cmp_eq_u32 s41, 28
	s_cselect_b32 s21, s11, s18
	s_cselect_b32 s20, s31, s3
	v_add_u32_e32 v152, s42, v155
	s_cselect_b32 s19, s9, s40
	s_cselect_b32 s18, s34, s35
	s_add_i32 s3, 0, 0x14000
	ds_read_b128 v[140:143], v152
	ds_read_b128 v[144:147], v152 offset:1024
	ds_read_b128 v[148:151], v152 offset:2048
	ds_read_b128 v[158:161], v152 offset:3072
	v_add_u32_e32 v152, s3, v155
	ds_read_b128 v[162:165], v152
	ds_read_b128 v[166:169], v152 offset:1024
	ds_read_b128 v[170:173], v152 offset:2048
	ds_read_b128 v[174:177], v152 offset:3072
	s_add_i32 m0, s22, 0xc000
	ds_read_b128 v[188:191], v157
	ds_read_b128 v[192:195], v157 offset:1024
	ds_read_b128 v[196:199], v157 offset:2048
	ds_read_b128 v[200:203], v157 offset:3072
	ds_read_b128 v[204:207], v157 offset:4096
	ds_read_b128 v[218:221], v157 offset:5120
	ds_read_b128 v[222:225], v157 offset:6144
	ds_read_b128 v[226:229], v157 offset:7168
	global_load_lds_dwordx4 v136, s[16:17]
	s_add_i32 m0, s22, 0xe000
	s_nop 0
	global_load_lds_dwordx4 v138, s[16:17]
	s_waitcnt vmcnt(8)
	s_waitcnt lgkmcnt(0)
	s_waitcnt lgkmcnt(0)
	v_mfma_f32_16x16x32_bf16 v[126:129], v[140:143], v[188:191], v[126:129]
	v_mfma_f32_16x16x32_bf16 v[122:125], v[148:151], v[188:191], v[122:125]
	s_barrier
	s_setprio 1
	v_mfma_f32_16x16x32_bf16 v[110:113], v[140:143], v[196:199], v[110:113]
	v_mfma_f32_16x16x32_bf16 v[106:109], v[148:151], v[196:199], v[106:109]
	v_mfma_f32_16x16x32_bf16 v[94:97], v[140:143], v[204:207], v[94:97]
	v_mfma_f32_16x16x32_bf16 v[90:93], v[148:151], v[204:207], v[90:93]
	v_mfma_f32_16x16x32_bf16 v[78:81], v[140:143], v[222:225], v[78:81]
	v_mfma_f32_16x16x32_bf16 v[74:77], v[148:151], v[222:225], v[74:77]
	v_mfma_f32_16x16x32_bf16 v[126:129], v[144:147], v[192:195], v[126:129]
	v_mfma_f32_16x16x32_bf16 v[122:125], v[158:161], v[192:195], v[122:125]
	v_mfma_f32_16x16x32_bf16 v[110:113], v[144:147], v[200:203], v[110:113]
	v_mfma_f32_16x16x32_bf16 v[106:109], v[158:161], v[200:203], v[106:109]
	v_mfma_f32_16x16x32_bf16 v[94:97], v[144:147], v[218:221], v[94:97]
	v_mfma_f32_16x16x32_bf16 v[90:93], v[158:161], v[218:221], v[90:93]
	v_mfma_f32_16x16x32_bf16 v[78:81], v[144:147], v[226:229], v[78:81]
	v_mfma_f32_16x16x32_bf16 v[74:77], v[158:161], v[226:229], v[74:77]
	s_setprio 0
	s_setprio 1
	v_mfma_f32_16x16x32_bf16 v[118:121], v[162:165], v[188:191], v[118:121]
	v_mfma_f32_16x16x32_bf16 v[114:117], v[170:173], v[188:191], v[114:117]
	v_mfma_f32_16x16x32_bf16 v[102:105], v[162:165], v[196:199], v[102:105]
	v_mfma_f32_16x16x32_bf16 v[98:101], v[170:173], v[196:199], v[98:101]
	v_mfma_f32_16x16x32_bf16 v[86:89], v[162:165], v[204:207], v[86:89]
	v_mfma_f32_16x16x32_bf16 v[82:85], v[170:173], v[204:207], v[82:85]
	v_mfma_f32_16x16x32_bf16 v[70:73], v[162:165], v[222:225], v[70:73]
	v_mfma_f32_16x16x32_bf16 v[66:69], v[170:173], v[222:225], v[66:69]
	v_mfma_f32_16x16x32_bf16 v[118:121], v[166:169], v[192:195], v[118:121]
	v_mfma_f32_16x16x32_bf16 v[114:117], v[174:177], v[192:195], v[114:117]
	v_mfma_f32_16x16x32_bf16 v[102:105], v[166:169], v[200:203], v[102:105]
	v_mfma_f32_16x16x32_bf16 v[98:101], v[174:177], v[200:203], v[98:101]
	v_mfma_f32_16x16x32_bf16 v[86:89], v[166:169], v[218:221], v[86:89]
	v_mfma_f32_16x16x32_bf16 v[82:85], v[174:177], v[218:221], v[82:85]
	v_mfma_f32_16x16x32_bf16 v[70:73], v[166:169], v[226:229], v[70:73]
	v_mfma_f32_16x16x32_bf16 v[66:69], v[174:177], v[226:229], v[66:69]
	s_setprio 0
	s_barrier
	s_add_i32 s42, s42, s2
	v_lshl_add_u64 v[152:153], s[18:19], 0, v[0:1]
	s_mov_b32 m0, s42
	ds_read_b128 v[188:191], v157 offset:16384
	ds_read_b128 v[192:195], v157 offset:17408
	ds_read_b128 v[196:199], v157 offset:18432
	ds_read_b128 v[200:203], v157 offset:19456
	ds_read_b128 v[204:207], v157 offset:20480
	ds_read_b128 v[218:221], v157 offset:21504
	ds_read_b128 v[222:225], v157 offset:22528
	ds_read_b128 v[226:229], v157 offset:23552
	global_load_lds_dwordx4 v[152:153], off
	s_add_i32 m0, s42, 0x2000
	s_add_u32 s44, s18, 0x80000
	v_lshl_add_u64 v[178:179], s[18:19], 0, v[130:131]
	s_addc_u32 s45, s19, 0
	s_add_i32 s3, s3, s2
	global_load_lds_dwordx4 v[178:179], off
	s_mov_b32 m0, s3
	v_lshl_add_u64 v[182:183], s[20:21], 0, v[132:133]
	global_load_lds_dwordx4 v0, s[44:45]
	s_add_i32 m0, s3, 0x2000
	s_nop 0
	global_load_lds_dwordx4 v130, s[44:45]
	v_lshl_add_u64 v[180:181], s[20:21], 0, v[134:135]
	s_mov_b32 m0, s22
	s_nop 0
	global_load_lds_dwordx4 v[180:181], off
	s_mov_b32 m0, s23
	s_nop 0
	global_load_lds_dwordx4 v[182:183], off
	s_waitcnt vmcnt(8)
	s_waitcnt lgkmcnt(0)
	s_waitcnt lgkmcnt(0)
	v_mfma_f32_16x16x32_bf16 v[62:65], v[140:143], v[188:191], v[62:65]
	v_mfma_f32_16x16x32_bf16 v[58:61], v[148:151], v[188:191], v[58:61]
	s_barrier
	s_setprio 1
	v_mfma_f32_16x16x32_bf16 v[46:49], v[140:143], v[196:199], v[46:49]
	v_mfma_f32_16x16x32_bf16 v[42:45], v[148:151], v[196:199], v[42:45]
	v_mfma_f32_16x16x32_bf16 v[30:33], v[140:143], v[204:207], v[30:33]
	v_mfma_f32_16x16x32_bf16 v[26:29], v[148:151], v[204:207], v[26:29]
	v_mfma_f32_16x16x32_bf16 v[14:17], v[140:143], v[222:225], v[14:17]
	v_mfma_f32_16x16x32_bf16 v[6:9], v[148:151], v[222:225], v[6:9]
	v_mfma_f32_16x16x32_bf16 v[62:65], v[144:147], v[192:195], v[62:65]
	v_mfma_f32_16x16x32_bf16 v[58:61], v[158:161], v[192:195], v[58:61]
	v_mfma_f32_16x16x32_bf16 v[46:49], v[144:147], v[200:203], v[46:49]
	v_mfma_f32_16x16x32_bf16 v[42:45], v[158:161], v[200:203], v[42:45]
	v_mfma_f32_16x16x32_bf16 v[30:33], v[144:147], v[218:221], v[30:33]
	v_mfma_f32_16x16x32_bf16 v[26:29], v[158:161], v[218:221], v[26:29]
	v_mfma_f32_16x16x32_bf16 v[14:17], v[144:147], v[226:229], v[14:17]
	v_mfma_f32_16x16x32_bf16 v[6:9], v[158:161], v[226:229], v[6:9]
	s_setprio 0
	s_setprio 1
	v_mfma_f32_16x16x32_bf16 v[54:57], v[162:165], v[188:191], v[54:57]
	v_mfma_f32_16x16x32_bf16 v[50:53], v[170:173], v[188:191], v[50:53]
	v_mfma_f32_16x16x32_bf16 v[38:41], v[162:165], v[196:199], v[38:41]
	v_mfma_f32_16x16x32_bf16 v[34:37], v[170:173], v[196:199], v[34:37]
	v_mfma_f32_16x16x32_bf16 v[22:25], v[162:165], v[204:207], v[22:25]
	v_mfma_f32_16x16x32_bf16 v[18:21], v[170:173], v[204:207], v[18:21]
	v_mfma_f32_16x16x32_bf16 v[10:13], v[162:165], v[222:225], v[10:13]
	v_mfma_f32_16x16x32_bf16 v[2:5], v[170:173], v[222:225], v[2:5]
	v_mfma_f32_16x16x32_bf16 v[54:57], v[166:169], v[192:195], v[54:57]
	v_mfma_f32_16x16x32_bf16 v[50:53], v[174:177], v[192:195], v[50:53]
	v_mfma_f32_16x16x32_bf16 v[38:41], v[166:169], v[200:203], v[38:41]
	v_mfma_f32_16x16x32_bf16 v[34:37], v[174:177], v[200:203], v[34:37]
	v_mfma_f32_16x16x32_bf16 v[22:25], v[166:169], v[218:221], v[22:25]
	v_mfma_f32_16x16x32_bf16 v[18:21], v[174:177], v[218:221], v[18:21]
	v_mfma_f32_16x16x32_bf16 v[10:13], v[166:169], v[226:229], v[10:13]
	v_mfma_f32_16x16x32_bf16 v[2:5], v[174:177], v[226:229], v[2:5]
	s_setprio 0
	s_barrier
	s_add_i32 s3, 0, 0x18000
	s_add_i32 s42, 0, 0x1c000
	v_add_u32_e32 v158, s3, v155
	v_add_u32_e32 v174, s42, v155
	ds_read_b128 v[140:143], v158
	ds_read_b128 v[144:147], v158 offset:1024
	ds_read_b128 v[148:151], v158 offset:2048
	ds_read_b128 v[158:161], v158 offset:3072
	ds_read_b128 v[162:165], v174
	ds_read_b128 v[166:169], v174 offset:1024
	ds_read_b128 v[170:173], v174 offset:2048
	ds_read_b128 v[174:177], v174 offset:3072
	s_add_u32 s20, s20, 0x80000
	s_addc_u32 s21, s21, 0
	s_mov_b32 m0, s24
	ds_read_b128 v[188:191], v157 offset:32768
	ds_read_b128 v[192:195], v157 offset:33792
	ds_read_b128 v[196:199], v157 offset:34816
	ds_read_b128 v[200:203], v157 offset:35840
	ds_read_b128 v[204:207], v157 offset:36864
	ds_read_b128 v[218:221], v157 offset:37888
	ds_read_b128 v[222:225], v157 offset:38912
	ds_read_b128 v[226:229], v157 offset:39936
	global_load_lds_dwordx4 v134, s[20:21]
	s_mov_b32 m0, s25
	s_nop 0
	global_load_lds_dwordx4 v132, s[20:21]
	s_waitcnt vmcnt(8)
	s_waitcnt lgkmcnt(0)
	s_waitcnt lgkmcnt(0)
	v_mfma_f32_16x16x32_bf16 v[126:129], v[140:143], v[188:191], v[126:129]
	v_mfma_f32_16x16x32_bf16 v[122:125], v[148:151], v[188:191], v[122:125]
	s_barrier
	s_setprio 1
	v_mfma_f32_16x16x32_bf16 v[110:113], v[140:143], v[196:199], v[110:113]
	v_mfma_f32_16x16x32_bf16 v[106:109], v[148:151], v[196:199], v[106:109]
	v_mfma_f32_16x16x32_bf16 v[94:97], v[140:143], v[204:207], v[94:97]
	v_mfma_f32_16x16x32_bf16 v[90:93], v[148:151], v[204:207], v[90:93]
	v_mfma_f32_16x16x32_bf16 v[78:81], v[140:143], v[222:225], v[78:81]
	v_mfma_f32_16x16x32_bf16 v[74:77], v[148:151], v[222:225], v[74:77]
	v_mfma_f32_16x16x32_bf16 v[126:129], v[144:147], v[192:195], v[126:129]
	v_mfma_f32_16x16x32_bf16 v[122:125], v[158:161], v[192:195], v[122:125]
	v_mfma_f32_16x16x32_bf16 v[110:113], v[144:147], v[200:203], v[110:113]
	v_mfma_f32_16x16x32_bf16 v[106:109], v[158:161], v[200:203], v[106:109]
	v_mfma_f32_16x16x32_bf16 v[94:97], v[144:147], v[218:221], v[94:97]
	v_mfma_f32_16x16x32_bf16 v[90:93], v[158:161], v[218:221], v[90:93]
	v_mfma_f32_16x16x32_bf16 v[78:81], v[144:147], v[226:229], v[78:81]
	v_mfma_f32_16x16x32_bf16 v[74:77], v[158:161], v[226:229], v[74:77]
	s_setprio 0
	s_setprio 1
	v_mfma_f32_16x16x32_bf16 v[118:121], v[162:165], v[188:191], v[118:121]
	v_mfma_f32_16x16x32_bf16 v[114:117], v[170:173], v[188:191], v[114:117]
	v_mfma_f32_16x16x32_bf16 v[102:105], v[162:165], v[196:199], v[102:105]
	v_mfma_f32_16x16x32_bf16 v[98:101], v[170:173], v[196:199], v[98:101]
	v_mfma_f32_16x16x32_bf16 v[86:89], v[162:165], v[204:207], v[86:89]
	v_mfma_f32_16x16x32_bf16 v[82:85], v[170:173], v[204:207], v[82:85]
	v_mfma_f32_16x16x32_bf16 v[70:73], v[162:165], v[222:225], v[70:73]
	v_mfma_f32_16x16x32_bf16 v[66:69], v[170:173], v[222:225], v[66:69]
	v_mfma_f32_16x16x32_bf16 v[118:121], v[166:169], v[192:195], v[118:121]
	v_mfma_f32_16x16x32_bf16 v[114:117], v[174:177], v[192:195], v[114:117]
	v_mfma_f32_16x16x32_bf16 v[102:105], v[166:169], v[200:203], v[102:105]
	v_mfma_f32_16x16x32_bf16 v[98:101], v[174:177], v[200:203], v[98:101]
	v_mfma_f32_16x16x32_bf16 v[86:89], v[166:169], v[218:221], v[86:89]
	v_mfma_f32_16x16x32_bf16 v[82:85], v[174:177], v[218:221], v[82:85]
	v_mfma_f32_16x16x32_bf16 v[70:73], v[166:169], v[226:229], v[70:73]
	v_mfma_f32_16x16x32_bf16 v[66:69], v[174:177], v[226:229], v[66:69]
	s_setprio 0
	s_barrier
	s_add_i32 s3, s3, s2
	v_lshl_add_u64 v[152:153], v[152:153], 0, s[52:53]
	s_mov_b32 m0, s3
	ds_read_b128 v[188:191], v157 offset:49152
	ds_read_b128 v[192:195], v157 offset:50176
	ds_read_b128 v[196:199], v157 offset:51200
	ds_read_b128 v[200:203], v157 offset:52224
	ds_read_b128 v[204:207], v157 offset:53248
	ds_read_b128 v[218:221], v157 offset:54272
	ds_read_b128 v[222:225], v157 offset:55296
	ds_read_b128 v[226:229], v157 offset:56320
	global_load_lds_dwordx4 v[152:153], off
	s_add_i32 m0, s3, 0x2000
	s_add_u32 s18, s18, 0x80080
	v_lshl_add_u64 v[152:153], v[178:179], 0, s[52:53]
	s_addc_u32 s19, s19, 0
	s_add_i32 s3, s42, s2
	global_load_lds_dwordx4 v[152:153], off
	s_mov_b32 m0, s3
	s_nop 0
	global_load_lds_dwordx4 v0, s[18:19]
	s_add_i32 m0, s3, 0x2000
	s_nop 0
	global_load_lds_dwordx4 v130, s[18:19]
	v_lshl_add_u64 v[152:153], v[180:181], 0, s[52:53]
	s_mov_b32 m0, s26
	s_nop 0
	global_load_lds_dwordx4 v[152:153], off
	v_lshl_add_u64 v[152:153], v[182:183], 0, s[52:53]
	s_mov_b32 m0, s27
	s_nop 0
	global_load_lds_dwordx4 v[152:153], off
	s_waitcnt vmcnt(8)
	s_waitcnt lgkmcnt(0)
	s_waitcnt lgkmcnt(0)
	v_mfma_f32_16x16x32_bf16 v[62:65], v[140:143], v[188:191], v[62:65]
	v_mfma_f32_16x16x32_bf16 v[58:61], v[148:151], v[188:191], v[58:61]
	s_barrier
	s_setprio 1
	v_mfma_f32_16x16x32_bf16 v[46:49], v[140:143], v[196:199], v[46:49]
	v_mfma_f32_16x16x32_bf16 v[42:45], v[148:151], v[196:199], v[42:45]
	v_mfma_f32_16x16x32_bf16 v[30:33], v[140:143], v[204:207], v[30:33]
	v_mfma_f32_16x16x32_bf16 v[26:29], v[148:151], v[204:207], v[26:29]
	v_mfma_f32_16x16x32_bf16 v[14:17], v[140:143], v[222:225], v[14:17]
	v_mfma_f32_16x16x32_bf16 v[6:9], v[148:151], v[222:225], v[6:9]
	v_mfma_f32_16x16x32_bf16 v[62:65], v[144:147], v[192:195], v[62:65]
	v_mfma_f32_16x16x32_bf16 v[58:61], v[158:161], v[192:195], v[58:61]
	v_mfma_f32_16x16x32_bf16 v[46:49], v[144:147], v[200:203], v[46:49]
	v_mfma_f32_16x16x32_bf16 v[42:45], v[158:161], v[200:203], v[42:45]
	v_mfma_f32_16x16x32_bf16 v[30:33], v[144:147], v[218:221], v[30:33]
	v_mfma_f32_16x16x32_bf16 v[26:29], v[158:161], v[218:221], v[26:29]
	v_mfma_f32_16x16x32_bf16 v[14:17], v[144:147], v[226:229], v[14:17]
	v_mfma_f32_16x16x32_bf16 v[6:9], v[158:161], v[226:229], v[6:9]
	s_setprio 0
	s_setprio 1
	v_mfma_f32_16x16x32_bf16 v[54:57], v[162:165], v[188:191], v[54:57]
	v_mfma_f32_16x16x32_bf16 v[50:53], v[170:173], v[188:191], v[50:53]
	v_mfma_f32_16x16x32_bf16 v[38:41], v[162:165], v[196:199], v[38:41]
	v_mfma_f32_16x16x32_bf16 v[34:37], v[170:173], v[196:199], v[34:37]
	v_mfma_f32_16x16x32_bf16 v[22:25], v[162:165], v[204:207], v[22:25]
	v_mfma_f32_16x16x32_bf16 v[18:21], v[170:173], v[204:207], v[18:21]
	v_mfma_f32_16x16x32_bf16 v[10:13], v[162:165], v[222:225], v[10:13]
	v_mfma_f32_16x16x32_bf16 v[2:5], v[170:173], v[222:225], v[2:5]
	v_mfma_f32_16x16x32_bf16 v[54:57], v[166:169], v[192:195], v[54:57]
	v_mfma_f32_16x16x32_bf16 v[50:53], v[174:177], v[192:195], v[50:53]
	v_mfma_f32_16x16x32_bf16 v[38:41], v[166:169], v[200:203], v[38:41]
	v_mfma_f32_16x16x32_bf16 v[34:37], v[174:177], v[200:203], v[34:37]
	v_mfma_f32_16x16x32_bf16 v[22:25], v[166:169], v[218:221], v[22:25]
	v_mfma_f32_16x16x32_bf16 v[18:21], v[174:177], v[218:221], v[18:21]
	v_mfma_f32_16x16x32_bf16 v[10:13], v[166:169], v[226:229], v[10:13]
	v_mfma_f32_16x16x32_bf16 v[2:5], v[174:177], v[226:229], v[2:5]
	s_setprio 0
	s_barrier
	s_add_i32 s41, s41, 2
	s_add_u32 s16, s16, 0x100
	s_addc_u32 s17, s17, 0
	s_add_u32 s35, s35, 0x100
	s_addc_u32 s40, s40, 0
	s_cmp_gt_u32 s41, 29
	s_cbranch_scc0 .LBB0_377
	s_and_b64 vcc, exec, s[6:7]
	s_movk_i32 s40, 0x4000
	s_movk_i32 s41, 0x6000
	s_cbranch_vccz .LBB0_380
	s_barrier

.LBB0_389:
	v_readlane_b32 s8, v254, 60
	v_mov_b32_e32 v167, v1
	v_readlane_b32 s9, v254, 61
	v_mov_b32_e32 v163, v1
	v_readlane_b32 s6, v254, 38
	v_lshl_add_u64 v[8:9], s[8:9], 0, v[166:167]
	v_lshl_add_u64 v[10:11], s[8:9], 0, v[162:163]
	v_mov_b32_e32 v169, v1
	v_readlane_b32 s7, v254, 39
	s_add_i32 m0, s28, 0x18000
	v_lshl_add_u64 v[8:9], v[8:9], 0, s[52:53]
	v_lshl_add_u64 v[12:13], s[6:7], 0, v[168:169]
	v_mov_b32_e32 v165, v1
	s_waitcnt vmcnt(2)
	s_barrier
	global_load_lds_dwordx4 v[8:9], off
	v_lshl_add_u64 v[8:9], v[10:11], 0, s[52:53]
	s_add_i32 m0, s28, 0x1a000
	s_add_i32 s35, s28, 0x8000
	v_lshl_add_u64 v[14:15], s[6:7], 0, v[164:165]
	global_load_lds_dwordx4 v[8:9], off
	v_lshl_add_u64 v[8:9], v[12:13], 0, s[52:53]
	s_mov_b32 m0, s35
	s_add_i32 s40, s28, 0xa000
	v_readlane_b32 s4, v254, 62
	global_load_lds_dwordx4 v[8:9], off
	v_lshl_add_u64 v[8:9], v[14:15], 0, s[52:53]
	s_mov_b32 m0, s40
	v_readlane_b32 s5, v254, 63
	global_load_lds_dwordx4 v[8:9], off
	s_add_i32 m0, s28, 0x1c000
	s_nop 0
	global_load_lds_dwordx4 v166, s[4:5]
	s_add_i32 m0, s28, 0x1e000
	v_bfe_u32 v204, v2, 4, 2
	global_load_lds_dwordx4 v162, s[4:5]
	v_and_b32_e32 v8, 15, v2
	v_lshlrev_b32_e32 v9, 4, v204
	v_lshlrev_b32_e32 v10, 2, v2
	s_and_b32 s3, s0, 3
	v_lshl_or_b32 v9, v8, 6, v9
	s_lshl_b32 s4, s34, 13
	v_and_b32_e32 v10, 32, v10
	v_bitop3_b32 v11, v9, s4, v10 bitop3:0xde
	s_lshl_b32 s4, s3, 5
	s_lshl_b32 s5, s3, 12
	s_cmpk_lt_u32 s1, 0x100
	s_cselect_b64 s[14:15], -1, 0
	s_bitcmp0_b32 s1, 6
	v_bitop3_b32 v206, v9, s5, v10 bitop3:0xde
	s_cselect_b64 s[16:17], -1, 0
	s_lshl_b32 s1, s34, 2
	v_add_u32_e32 v9, -12, v8
	v_and_b32_e32 v10, 7, v2
	s_or_b32 s1, s1, s3
	v_add_u32_e32 v10, 4, v10
	v_cmp_gt_u32_e32 vcc, -8, v9
	v_bfe_u32 v12, v2, 2, 4
	v_lshl_or_b32 v205, s34, 6, v8
	s_mulk_i32 s1, 0x900
	v_cndmask_b32_e32 v8, v10, v8, vcc
	v_and_b32_e32 v13, 3, v2
	s_lshl_b32 s0, s0, 5
	v_mov_b32_e32 v2, 0x6f
	v_or_b32_e32 v14, 16, v12
	v_mov_b32_e32 v10, 0x7f
	v_bitop3_b32 v2, s0, v2, v12 bitop3:0xc8
	v_bitop3_b32 v10, s0, v10, v14 bitop3:0xc8
	s_add_i32 s0, s1, 0
	v_lshlrev_b32_e32 v9, 1, v8
	v_mul_u32_u24_e32 v17, 0x240, v204
	s_add_i32 s0, s0, 0x20000
	v_add3_u32 v217, s0, v9, v17
	v_lshlrev_b32_e32 v9, 15, v6
	v_and_b32_e32 v9, 0xffff0000, v9
	v_lshl_add_u32 v5, v5, 12, v9
	v_and_b32_e32 v6, 1, v6
	v_lshl_or_b32 v5, v6, 6, v5
	v_lshl_add_u32 v170, v7, 1, v5
	v_lshlrev_b32_e32 v5, 15, v0
	v_and_b32_e32 v5, 0xffff0000, v5
	s_waitcnt vmcnt(6)
	v_lshlrev_b32_e32 v8, 3, v13
	v_or_b32_e32 v15, s4, v12
	v_or_b32_e32 v14, s4, v14
	v_lshl_add_u32 v13, v13, 4, s0
	v_lshl_add_u32 v3, v3, 12, v5
	v_and_b32_e32 v0, 1, v0
	v_readlane_b32 s0, v254, 36
	v_lshlrev_b32_e32 v2, 6, v2
	v_lshlrev_b32_e32 v10, 6, v10
	v_mul_u32_u24_e32 v16, 0x48, v12
	v_lshlrev_b32_e32 v12, 6, v15
	v_lshlrev_b32_e32 v14, 6, v14
	v_lshl_or_b32 v0, v0, 6, v3
	v_readlane_b32 s1, v254, 37
	s_mov_b32 s41, 0
	v_lshl_or_b32 v207, v204, 3, s4
	v_mov_b32_e32 v171, v1
	v_lshl_add_u32 v172, v4, 1, v0
	v_mov_b32_e32 v173, v1
	v_add_u32_e32 v218, 0, v11
	v_add_u32_e32 v219, v13, v16
	v_lshlrev_b32_e32 v174, 1, v12
	v_lshlrev_b32_e32 v188, 1, v8
	v_lshlrev_b32_e32 v190, 1, v14
	v_lshlrev_b32_e32 v192, 1, v2
	v_lshlrev_b32_e32 v194, 1, v10
	v_readlane_b32 s44, v254, 23
	s_mov_b32 s45, s0
	s_mov_b64 s[4:5], s[8:9]
	s_mov_b64 s[0:1], s[6:7]
	s_barrier
	s_branch .LBB0_392

.LBB0_399:
	s_add_u32 s3, s0, 0xfff80080
	s_addc_u32 s4, s1, -1
	s_add_i32 s42, 0, 0x10000
	s_cmp_eq_u32 s46, 28
	s_cselect_b32 s7, s8, s4
	s_cselect_b32 s6, s9, s3
	v_add_u32_e32 v0, s42, v206
	s_cselect_b32 s5, s19, s27
	s_cselect_b32 s4, s21, s26
	s_add_i32 s3, 0, 0x14000
	ds_read_b128 v[130:133], v0
	ds_read_b128 v[134:137], v0 offset:1024
	ds_read_b128 v[138:141], v0 offset:2048
	ds_read_b128 v[142:145], v0 offset:3072
	v_add_u32_e32 v0, s3, v206
	ds_read_b128 v[146:149], v0
	ds_read_b128 v[150:153], v0 offset:1024
	s_waitcnt lgkmcnt(0)
	ds_read_b128 v[154:157], v0 offset:2048
	ds_read_b128 v[158:161], v0 offset:3072
	s_add_i32 m0, s28, 0xc000
	ds_read_b128 v[196:199], v218
	ds_read_b128 v[200:203], v218 offset:1024
	ds_read_b128 v[220:223], v218 offset:2048
	ds_read_b128 v[224:227], v218 offset:3072
	ds_read_b128 v[228:231], v218 offset:4096
	ds_read_b128 v[232:235], v218 offset:5120
	ds_read_b128 v[236:239], v218 offset:6144
	ds_read_b128 v[240:243], v218 offset:7168
	global_load_lds_dwordx4 v170, s[0:1]
	s_add_i32 m0, s28, 0xe000
	s_nop 0
	global_load_lds_dwordx4 v172, s[0:1]
	s_waitcnt vmcnt(8)
	s_waitcnt lgkmcnt(0)
	s_waitcnt lgkmcnt(0)
	v_mfma_f32_16x16x32_bf16 v[126:129], v[130:133], v[196:199], v[126:129]
	v_mfma_f32_16x16x32_bf16 v[122:125], v[138:141], v[196:199], v[122:125]
	s_barrier
	s_setprio 1
	v_mfma_f32_16x16x32_bf16 v[118:121], v[130:133], v[220:223], v[118:121]
	v_mfma_f32_16x16x32_bf16 v[114:117], v[138:141], v[220:223], v[114:117]
	v_mfma_f32_16x16x32_bf16 v[110:113], v[130:133], v[228:231], v[110:113]
	v_mfma_f32_16x16x32_bf16 v[106:109], v[138:141], v[228:231], v[106:109]
	v_mfma_f32_16x16x32_bf16 v[102:105], v[130:133], v[236:239], v[102:105]
	v_mfma_f32_16x16x32_bf16 v[98:101], v[138:141], v[236:239], v[98:101]
	v_mfma_f32_16x16x32_bf16 v[126:129], v[134:137], v[200:203], v[126:129]
	v_mfma_f32_16x16x32_bf16 v[122:125], v[142:145], v[200:203], v[122:125]
	v_mfma_f32_16x16x32_bf16 v[118:121], v[134:137], v[224:227], v[118:121]
	v_mfma_f32_16x16x32_bf16 v[114:117], v[142:145], v[224:227], v[114:117]
	v_mfma_f32_16x16x32_bf16 v[110:113], v[134:137], v[232:235], v[110:113]
	v_mfma_f32_16x16x32_bf16 v[106:109], v[142:145], v[232:235], v[106:109]
	v_mfma_f32_16x16x32_bf16 v[102:105], v[134:137], v[240:243], v[102:105]
	v_mfma_f32_16x16x32_bf16 v[98:101], v[142:145], v[240:243], v[98:101]
	s_setprio 0
	s_setprio 1
	v_mfma_f32_16x16x32_bf16 v[94:97], v[146:149], v[196:199], v[94:97]
	v_mfma_f32_16x16x32_bf16 v[90:93], v[154:157], v[196:199], v[90:93]
	v_mfma_f32_16x16x32_bf16 v[86:89], v[146:149], v[220:223], v[86:89]
	v_mfma_f32_16x16x32_bf16 v[82:85], v[154:157], v[220:223], v[82:85]
	v_mfma_f32_16x16x32_bf16 v[78:81], v[146:149], v[228:231], v[78:81]
	v_mfma_f32_16x16x32_bf16 v[74:77], v[154:157], v[228:231], v[74:77]
	v_mfma_f32_16x16x32_bf16 v[70:73], v[146:149], v[236:239], v[70:73]
	v_mfma_f32_16x16x32_bf16 v[66:69], v[154:157], v[236:239], v[66:69]
	v_mfma_f32_16x16x32_bf16 v[94:97], v[150:153], v[200:203], v[94:97]
	v_mfma_f32_16x16x32_bf16 v[90:93], v[158:161], v[200:203], v[90:93]
	v_mfma_f32_16x16x32_bf16 v[86:89], v[150:153], v[224:227], v[86:89]
	v_mfma_f32_16x16x32_bf16 v[82:85], v[158:161], v[224:227], v[82:85]
	v_mfma_f32_16x16x32_bf16 v[78:81], v[150:153], v[232:235], v[78:81]
	v_mfma_f32_16x16x32_bf16 v[74:77], v[158:161], v[232:235], v[74:77]
	v_mfma_f32_16x16x32_bf16 v[70:73], v[150:153], v[240:243], v[70:73]
	v_mfma_f32_16x16x32_bf16 v[66:69], v[158:161], v[240:243], v[66:69]
	s_setprio 0
	s_barrier
	s_add_i32 s42, s42, s2
	v_lshl_add_u64 v[176:177], s[4:5], 0, v[166:167]
	s_mov_b32 m0, s42
	ds_read_b128 v[196:199], v218 offset:16384
	ds_read_b128 v[200:203], v218 offset:17408
	ds_read_b128 v[220:223], v218 offset:18432
	ds_read_b128 v[224:227], v218 offset:19456
	ds_read_b128 v[228:231], v218 offset:20480
	ds_read_b128 v[232:235], v218 offset:21504
	ds_read_b128 v[236:239], v218 offset:22528
	ds_read_b128 v[240:243], v218 offset:23552
	global_load_lds_dwordx4 v[176:177], off
	s_add_i32 m0, s42, 0x2000
	s_add_u32 s56, s4, 0x80000
	v_lshl_add_u64 v[178:179], s[4:5], 0, v[162:163]
	s_addc_u32 s57, s5, 0
	s_add_i32 s3, s3, s2
	global_load_lds_dwordx4 v[178:179], off
	s_mov_b32 m0, s3
	v_lshl_add_u64 v[246:247], s[6:7], 0, v[164:165]
	global_load_lds_dwordx4 v166, s[56:57]
	s_add_i32 m0, s3, 0x2000
	s_nop 0
	global_load_lds_dwordx4 v162, s[56:57]
	v_lshl_add_u64 v[244:245], s[6:7], 0, v[168:169]
	s_mov_b32 m0, s28
	s_nop 0
	global_load_lds_dwordx4 v[244:245], off
	s_mov_b32 m0, s29
	s_nop 0
	global_load_lds_dwordx4 v[246:247], off
	s_waitcnt vmcnt(8)
	s_waitcnt lgkmcnt(0)
	s_waitcnt lgkmcnt(0)
	v_mfma_f32_16x16x32_bf16 v[62:65], v[130:133], v[196:199], v[62:65]
	v_mfma_f32_16x16x32_bf16 v[58:61], v[138:141], v[196:199], v[58:61]
	s_barrier
	s_setprio 1
	v_mfma_f32_16x16x32_bf16 v[54:57], v[130:133], v[220:223], v[54:57]
	v_mfma_f32_16x16x32_bf16 v[50:53], v[138:141], v[220:223], v[50:53]
	v_mfma_f32_16x16x32_bf16 v[46:49], v[130:133], v[228:231], v[46:49]
	v_mfma_f32_16x16x32_bf16 v[42:45], v[138:141], v[228:231], v[42:45]
	v_mfma_f32_16x16x32_bf16 v[38:41], v[130:133], v[236:239], v[38:41]
	v_mfma_f32_16x16x32_bf16 v[34:37], v[138:141], v[236:239], v[34:37]
	v_mfma_f32_16x16x32_bf16 v[62:65], v[134:137], v[200:203], v[62:65]
	v_mfma_f32_16x16x32_bf16 v[58:61], v[142:145], v[200:203], v[58:61]
	v_mfma_f32_16x16x32_bf16 v[54:57], v[134:137], v[224:227], v[54:57]
	v_mfma_f32_16x16x32_bf16 v[50:53], v[142:145], v[224:227], v[50:53]
	v_mfma_f32_16x16x32_bf16 v[46:49], v[134:137], v[232:235], v[46:49]
	v_mfma_f32_16x16x32_bf16 v[42:45], v[142:145], v[232:235], v[42:45]
	v_mfma_f32_16x16x32_bf16 v[38:41], v[134:137], v[240:243], v[38:41]
	v_mfma_f32_16x16x32_bf16 v[34:37], v[142:145], v[240:243], v[34:37]
	s_setprio 0
	s_setprio 1
	v_mfma_f32_16x16x32_bf16 v[30:33], v[146:149], v[196:199], v[30:33]
	v_mfma_f32_16x16x32_bf16 v[26:29], v[154:157], v[196:199], v[26:29]
	v_mfma_f32_16x16x32_bf16 v[22:25], v[146:149], v[220:223], v[22:25]
	v_mfma_f32_16x16x32_bf16 v[18:21], v[154:157], v[220:223], v[18:21]
	v_mfma_f32_16x16x32_bf16 v[14:17], v[146:149], v[228:231], v[14:17]
	v_mfma_f32_16x16x32_bf16 v[10:13], v[154:157], v[228:231], v[10:13]
	v_mfma_f32_16x16x32_bf16 v[6:9], v[146:149], v[236:239], v[6:9]
	v_mfma_f32_16x16x32_bf16 v[2:5], v[154:157], v[236:239], v[2:5]
	v_mfma_f32_16x16x32_bf16 v[30:33], v[150:153], v[200:203], v[30:33]
	v_mfma_f32_16x16x32_bf16 v[26:29], v[158:161], v[200:203], v[26:29]
	v_mfma_f32_16x16x32_bf16 v[22:25], v[150:153], v[224:227], v[22:25]
	v_mfma_f32_16x16x32_bf16 v[18:21], v[158:161], v[224:227], v[18:21]
	v_mfma_f32_16x16x32_bf16 v[14:17], v[150:153], v[232:235], v[14:17]
	v_mfma_f32_16x16x32_bf16 v[10:13], v[158:161], v[232:235], v[10:13]
	v_mfma_f32_16x16x32_bf16 v[6:9], v[150:153], v[240:243], v[6:9]
	v_mfma_f32_16x16x32_bf16 v[2:5], v[158:161], v[240:243], v[2:5]
	s_setprio 0
	s_barrier
	s_add_i32 s3, 0, 0x18000
	v_add_u32_e32 v0, s3, v206
	s_add_i32 s42, 0, 0x1c000
	ds_read_b128 v[130:133], v0
	ds_read_b128 v[134:137], v0 offset:1024
	ds_read_b128 v[138:141], v0 offset:2048
	ds_read_b128 v[142:145], v0 offset:3072
	v_add_u32_e32 v0, s42, v206
	ds_read_b128 v[146:149], v0
	ds_read_b128 v[150:153], v0 offset:1024
	ds_read_b128 v[154:157], v0 offset:2048
	ds_read_b128 v[158:161], v0 offset:3072
	s_add_u32 s6, s6, 0x80000
	s_addc_u32 s7, s7, 0
	s_mov_b32 m0, s30
	ds_read_b128 v[196:199], v218 offset:32768
	ds_read_b128 v[200:203], v218 offset:33792
	ds_read_b128 v[220:223], v218 offset:34816
	ds_read_b128 v[224:227], v218 offset:35840
	ds_read_b128 v[228:231], v218 offset:36864
	ds_read_b128 v[232:235], v218 offset:37888
	ds_read_b128 v[236:239], v218 offset:38912
	ds_read_b128 v[240:243], v218 offset:39936
	global_load_lds_dwordx4 v168, s[6:7]
	s_mov_b32 m0, s31
	s_nop 0
	global_load_lds_dwordx4 v164, s[6:7]
	s_waitcnt vmcnt(8)
	s_waitcnt lgkmcnt(0)
	s_waitcnt lgkmcnt(0)
	v_mfma_f32_16x16x32_bf16 v[126:129], v[130:133], v[196:199], v[126:129]
	v_mfma_f32_16x16x32_bf16 v[122:125], v[138:141], v[196:199], v[122:125]
	s_barrier
	s_setprio 1
	v_mfma_f32_16x16x32_bf16 v[118:121], v[130:133], v[220:223], v[118:121]
	v_mfma_f32_16x16x32_bf16 v[114:117], v[138:141], v[220:223], v[114:117]
	v_mfma_f32_16x16x32_bf16 v[110:113], v[130:133], v[228:231], v[110:113]
	v_mfma_f32_16x16x32_bf16 v[106:109], v[138:141], v[228:231], v[106:109]
	v_mfma_f32_16x16x32_bf16 v[102:105], v[130:133], v[236:239], v[102:105]
	v_mfma_f32_16x16x32_bf16 v[98:101], v[138:141], v[236:239], v[98:101]
	v_mfma_f32_16x16x32_bf16 v[126:129], v[134:137], v[200:203], v[126:129]
	v_mfma_f32_16x16x32_bf16 v[122:125], v[142:145], v[200:203], v[122:125]
	v_mfma_f32_16x16x32_bf16 v[118:121], v[134:137], v[224:227], v[118:121]
	v_mfma_f32_16x16x32_bf16 v[114:117], v[142:145], v[224:227], v[114:117]
	v_mfma_f32_16x16x32_bf16 v[110:113], v[134:137], v[232:235], v[110:113]
	v_mfma_f32_16x16x32_bf16 v[106:109], v[142:145], v[232:235], v[106:109]
	v_mfma_f32_16x16x32_bf16 v[102:105], v[134:137], v[240:243], v[102:105]
	v_mfma_f32_16x16x32_bf16 v[98:101], v[142:145], v[240:243], v[98:101]
	s_setprio 0
	s_setprio 1
	v_mfma_f32_16x16x32_bf16 v[94:97], v[146:149], v[196:199], v[94:97]
	v_mfma_f32_16x16x32_bf16 v[90:93], v[154:157], v[196:199], v[90:93]
	v_mfma_f32_16x16x32_bf16 v[86:89], v[146:149], v[220:223], v[86:89]
	v_mfma_f32_16x16x32_bf16 v[82:85], v[154:157], v[220:223], v[82:85]
	v_mfma_f32_16x16x32_bf16 v[78:81], v[146:149], v[228:231], v[78:81]
	v_mfma_f32_16x16x32_bf16 v[74:77], v[154:157], v[228:231], v[74:77]
	v_mfma_f32_16x16x32_bf16 v[70:73], v[146:149], v[236:239], v[70:73]
	v_mfma_f32_16x16x32_bf16 v[66:69], v[154:157], v[236:239], v[66:69]
	v_mfma_f32_16x16x32_bf16 v[94:97], v[150:153], v[200:203], v[94:97]
	v_mfma_f32_16x16x32_bf16 v[90:93], v[158:161], v[200:203], v[90:93]
	v_mfma_f32_16x16x32_bf16 v[86:89], v[150:153], v[224:227], v[86:89]
	v_mfma_f32_16x16x32_bf16 v[82:85], v[158:161], v[224:227], v[82:85]
	v_mfma_f32_16x16x32_bf16 v[78:81], v[150:153], v[232:235], v[78:81]
	v_mfma_f32_16x16x32_bf16 v[74:77], v[158:161], v[232:235], v[74:77]
	v_mfma_f32_16x16x32_bf16 v[70:73], v[150:153], v[240:243], v[70:73]
	v_mfma_f32_16x16x32_bf16 v[66:69], v[158:161], v[240:243], v[66:69]
	s_setprio 0
	s_barrier
	s_add_i32 s3, s3, s2
	v_lshl_add_u64 v[176:177], v[176:177], 0, s[52:53]
	s_mov_b32 m0, s3
	ds_read_b128 v[196:199], v218 offset:49152
	ds_read_b128 v[200:203], v218 offset:50176
	ds_read_b128 v[220:223], v218 offset:51200
	ds_read_b128 v[224:227], v218 offset:52224
	ds_read_b128 v[228:231], v218 offset:53248
	ds_read_b128 v[232:235], v218 offset:54272
	ds_read_b128 v[236:239], v218 offset:55296
	ds_read_b128 v[240:243], v218 offset:56320
	global_load_lds_dwordx4 v[176:177], off
	s_add_i32 m0, s3, 0x2000
	s_add_u32 s4, s4, 0x80080
	v_lshl_add_u64 v[176:177], v[178:179], 0, s[52:53]
	s_addc_u32 s5, s5, 0
	s_add_i32 s3, s42, s2
	global_load_lds_dwordx4 v[176:177], off
	s_mov_b32 m0, s3
	s_nop 0
	global_load_lds_dwordx4 v166, s[4:5]
	s_add_i32 m0, s3, 0x2000
	s_nop 0
	global_load_lds_dwordx4 v162, s[4:5]
	v_lshl_add_u64 v[176:177], v[244:245], 0, s[52:53]
	s_mov_b32 m0, s35
	s_nop 0
	global_load_lds_dwordx4 v[176:177], off
	v_lshl_add_u64 v[176:177], v[246:247], 0, s[52:53]
	s_mov_b32 m0, s40
	s_nop 0
	global_load_lds_dwordx4 v[176:177], off
	s_waitcnt vmcnt(8)
	s_waitcnt lgkmcnt(0)
	s_waitcnt lgkmcnt(0)
	v_mfma_f32_16x16x32_bf16 v[62:65], v[130:133], v[196:199], v[62:65]
	v_mfma_f32_16x16x32_bf16 v[58:61], v[138:141], v[196:199], v[58:61]
	s_barrier
	s_setprio 1
	v_mfma_f32_16x16x32_bf16 v[54:57], v[130:133], v[220:223], v[54:57]
	v_mfma_f32_16x16x32_bf16 v[50:53], v[138:141], v[220:223], v[50:53]
	v_mfma_f32_16x16x32_bf16 v[46:49], v[130:133], v[228:231], v[46:49]
	v_mfma_f32_16x16x32_bf16 v[42:45], v[138:141], v[228:231], v[42:45]
	v_mfma_f32_16x16x32_bf16 v[38:41], v[130:133], v[236:239], v[38:41]
	v_mfma_f32_16x16x32_bf16 v[34:37], v[138:141], v[236:239], v[34:37]
	v_mfma_f32_16x16x32_bf16 v[62:65], v[134:137], v[200:203], v[62:65]
	v_mfma_f32_16x16x32_bf16 v[58:61], v[142:145], v[200:203], v[58:61]
	v_mfma_f32_16x16x32_bf16 v[54:57], v[134:137], v[224:227], v[54:57]
	v_mfma_f32_16x16x32_bf16 v[50:53], v[142:145], v[224:227], v[50:53]
	v_mfma_f32_16x16x32_bf16 v[46:49], v[134:137], v[232:235], v[46:49]
	v_mfma_f32_16x16x32_bf16 v[42:45], v[142:145], v[232:235], v[42:45]
	v_mfma_f32_16x16x32_bf16 v[38:41], v[134:137], v[240:243], v[38:41]
	v_mfma_f32_16x16x32_bf16 v[34:37], v[142:145], v[240:243], v[34:37]
	s_setprio 0
	s_setprio 1
	v_mfma_f32_16x16x32_bf16 v[30:33], v[146:149], v[196:199], v[30:33]
	v_mfma_f32_16x16x32_bf16 v[26:29], v[154:157], v[196:199], v[26:29]
	v_mfma_f32_16x16x32_bf16 v[22:25], v[146:149], v[220:223], v[22:25]
	v_mfma_f32_16x16x32_bf16 v[18:21], v[154:157], v[220:223], v[18:21]
	v_mfma_f32_16x16x32_bf16 v[14:17], v[146:149], v[228:231], v[14:17]
	v_mfma_f32_16x16x32_bf16 v[10:13], v[154:157], v[228:231], v[10:13]
	v_mfma_f32_16x16x32_bf16 v[6:9], v[146:149], v[236:239], v[6:9]
	v_mfma_f32_16x16x32_bf16 v[2:5], v[154:157], v[236:239], v[2:5]
	v_mfma_f32_16x16x32_bf16 v[30:33], v[150:153], v[200:203], v[30:33]
	v_mfma_f32_16x16x32_bf16 v[26:29], v[158:161], v[200:203], v[26:29]
	v_mfma_f32_16x16x32_bf16 v[22:25], v[150:153], v[224:227], v[22:25]
	v_mfma_f32_16x16x32_bf16 v[18:21], v[158:161], v[224:227], v[18:21]
	v_mfma_f32_16x16x32_bf16 v[14:17], v[150:153], v[232:235], v[14:17]
	v_mfma_f32_16x16x32_bf16 v[10:13], v[158:161], v[232:235], v[10:13]
	v_mfma_f32_16x16x32_bf16 v[6:9], v[150:153], v[240:243], v[6:9]
	v_mfma_f32_16x16x32_bf16 v[2:5], v[158:161], v[240:243], v[2:5]
	s_setprio 0
	s_barrier
	s_add_i32 s46, s46, 2
	s_add_u32 s0, s0, 0x100
	s_addc_u32 s1, s1, 0
	s_add_u32 s26, s26, 0x100
	s_addc_u32 s27, s27, 0
	s_cmp_gt_u32 s46, 29
	s_cbranch_scc0 .LBB0_399
	s_and_b64 vcc, exec, s[14:15]
	s_cbranch_vccz .LBB0_402
	s_barrier

.LBB0_836:
	v_lshrrev_b32_e32 v18, 1, v8
	v_and_b32_e32 v18, 24, v18
	v_readlane_b32 s18, v254, 32
	v_and_b32_e32 v9, 15, v8
	v_lshlrev_b32_e32 v19, 1, v18
	v_lshlrev_b32_e32 v8, 2, v8
	s_lshl_b32 s1, s1, 5
	v_readlane_b32 s19, v254, 33
	v_lshl_or_b32 v162, s4, 6, v9
	v_lshl_or_b32 v9, v9, 6, v19
	s_lshl_b32 s3, s4, 13
	v_and_b32_e32 v8, 32, v8
	s_and_b32 s1, s1, 0x60
	v_lshl_add_u64 v[10:11], s[18:19], 0, v[0:1]
	v_mov_b32_e32 v131, v1
	v_readlane_b32 s14, v254, 28
	v_bitop3_b32 v19, v9, s3, v8 bitop3:0xde
	s_lshl_b32 s3, s1, 7
	v_lshl_add_u64 v[12:13], s[18:19], 0, v[130:131]
	v_mov_b32_e32 v135, v1
	v_readlane_b32 s15, v254, 29
	v_bitop3_b32 v163, v9, s3, v8 bitop3:0xde
	s_add_i32 m0, s22, 0x18000
	v_lshl_add_u64 v[8:9], v[10:11], 0, s[52:53]
	v_lshl_add_u64 v[14:15], s[14:15], 0, v[134:135]
	v_mov_b32_e32 v133, v1
	s_waitcnt vmcnt(2)
	s_barrier
	global_load_lds_dwordx4 v[8:9], off
	v_lshl_add_u64 v[8:9], v[12:13], 0, s[52:53]
	s_add_i32 m0, s22, 0x1a000
	s_add_i32 s26, s22, 0x8000
	v_lshl_add_u64 v[16:17], s[14:15], 0, v[132:133]
	global_load_lds_dwordx4 v[8:9], off
	v_lshl_add_u64 v[8:9], v[14:15], 0, s[52:53]
	s_mov_b32 m0, s26
	s_add_i32 s27, s22, 0xa000
	v_readlane_b32 s4, v254, 34
	global_load_lds_dwordx4 v[8:9], off
	v_lshl_add_u64 v[8:9], v[16:17], 0, s[52:53]
	s_mov_b32 m0, s27
	v_readlane_b32 s5, v254, 35
	global_load_lds_dwordx4 v[8:9], off
	s_add_i32 m0, s22, 0x1c000
	s_nop 0
	global_load_lds_dwordx4 v0, s[4:5]
	s_add_i32 m0, s22, 0x1e000
	s_cmpk_lt_u32 s0, 0x100
	global_load_lds_dwordx4 v130, s[4:5]
	v_lshlrev_b32_e32 v8, 15, v6
	v_and_b32_e32 v8, 0xffff0000, v8
	v_lshl_add_u32 v5, v5, 12, v8
	v_and_b32_e32 v6, 1, v6
	v_lshl_or_b32 v5, v6, 6, v5
	v_lshl_add_u32 v136, v7, 1, v5
	v_lshlrev_b32_e32 v5, 15, v2
	v_and_b32_e32 v5, 0xffff0000, v5
	s_waitcnt vmcnt(6)
	v_or_b32_e32 v164, s1, v18
	v_lshl_add_u32 v3, v3, 12, v5
	v_and_b32_e32 v2, 1, v2
	v_readlane_b32 s0, v254, 44
	v_lshl_or_b32 v2, v2, 6, v3
	v_readlane_b32 s1, v254, 45
	s_cselect_b64 s[8:9], -1, 0
	v_mov_b32_e32 v137, v1
	v_lshl_add_u32 v138, v4, 1, v2
	v_mov_b32_e32 v139, v1
	s_mov_b32 s28, 0
	v_add_u32_e32 v165, 0, v19
	v_readlane_b32 s30, v254, 22
	s_mov_b32 s29, s0
	s_mov_b64 s[0:1], s[14:15]
	s_barrier
	s_branch .LBB0_839

.LBB0_846:
	s_add_u32 s3, s0, 0xfff80080
	s_addc_u32 s18, s1, -1
	s_add_i32 s42, 0, 0x10000
	s_cmp_eq_u32 s41, 28
	s_cselect_b32 s21, s13, s18
	s_cselect_b32 s20, s31, s3
	s_cselect_b32 s19, s11, s40
	s_cselect_b32 s18, s34, s35
	s_add_i32 s3, 0, 0x14000
	v_add_u32_e32 v152, s42, v163
	v_add_u32_e32 v160, s3, v163
	ds_read_b128 v[140:143], v152
	ds_read_b128 v[144:147], v152 offset:1024
	ds_read_b128 v[148:151], v152 offset:2048
	ds_read_b128 v[152:155], v152 offset:3072
	ds_read_b128 v[156:159], v160
	ds_read_b128 v[166:169], v160 offset:1024
	ds_read_b128 v[170:173], v160 offset:2048
	ds_read_b128 v[174:177], v160 offset:3072
	s_add_i32 m0, s22, 0xc000
	ds_read_b128 v[188:191], v165
	ds_read_b128 v[192:195], v165 offset:1024
	ds_read_b128 v[196:199], v165 offset:2048
	ds_read_b128 v[200:203], v165 offset:3072
	ds_read_b128 v[204:207], v165 offset:4096
	ds_read_b128 v[218:221], v165 offset:5120
	ds_read_b128 v[222:225], v165 offset:6144
	ds_read_b128 v[226:229], v165 offset:7168
	global_load_lds_dwordx4 v136, s[0:1]
	s_add_i32 m0, s22, 0xe000
	s_nop 0
	global_load_lds_dwordx4 v138, s[0:1]
	s_waitcnt vmcnt(8)
	s_waitcnt lgkmcnt(0)
	s_waitcnt lgkmcnt(0)
	v_mfma_f32_16x16x32_bf16 v[126:129], v[140:143], v[188:191], v[126:129]
	v_mfma_f32_16x16x32_bf16 v[122:125], v[148:151], v[188:191], v[122:125]
	s_barrier
	s_setprio 1
	v_mfma_f32_16x16x32_bf16 v[110:113], v[140:143], v[196:199], v[110:113]
	v_mfma_f32_16x16x32_bf16 v[106:109], v[148:151], v[196:199], v[106:109]
	v_mfma_f32_16x16x32_bf16 v[94:97], v[140:143], v[204:207], v[94:97]
	v_mfma_f32_16x16x32_bf16 v[90:93], v[148:151], v[204:207], v[90:93]
	v_mfma_f32_16x16x32_bf16 v[78:81], v[140:143], v[222:225], v[78:81]
	v_mfma_f32_16x16x32_bf16 v[74:77], v[148:151], v[222:225], v[74:77]
	v_mfma_f32_16x16x32_bf16 v[126:129], v[144:147], v[192:195], v[126:129]
	v_mfma_f32_16x16x32_bf16 v[122:125], v[152:155], v[192:195], v[122:125]
	v_mfma_f32_16x16x32_bf16 v[110:113], v[144:147], v[200:203], v[110:113]
	v_mfma_f32_16x16x32_bf16 v[106:109], v[152:155], v[200:203], v[106:109]
	v_mfma_f32_16x16x32_bf16 v[94:97], v[144:147], v[218:221], v[94:97]
	v_mfma_f32_16x16x32_bf16 v[90:93], v[152:155], v[218:221], v[90:93]
	v_mfma_f32_16x16x32_bf16 v[78:81], v[144:147], v[226:229], v[78:81]
	v_mfma_f32_16x16x32_bf16 v[74:77], v[152:155], v[226:229], v[74:77]
	s_setprio 0
	s_setprio 1
	v_mfma_f32_16x16x32_bf16 v[118:121], v[156:159], v[188:191], v[118:121]
	v_mfma_f32_16x16x32_bf16 v[114:117], v[170:173], v[188:191], v[114:117]
	v_mfma_f32_16x16x32_bf16 v[102:105], v[156:159], v[196:199], v[102:105]
	v_mfma_f32_16x16x32_bf16 v[98:101], v[170:173], v[196:199], v[98:101]
	v_mfma_f32_16x16x32_bf16 v[86:89], v[156:159], v[204:207], v[86:89]
	v_mfma_f32_16x16x32_bf16 v[82:85], v[170:173], v[204:207], v[82:85]
	v_mfma_f32_16x16x32_bf16 v[70:73], v[156:159], v[222:225], v[70:73]
	v_mfma_f32_16x16x32_bf16 v[66:69], v[170:173], v[222:225], v[66:69]
	v_mfma_f32_16x16x32_bf16 v[118:121], v[166:169], v[192:195], v[118:121]
	v_mfma_f32_16x16x32_bf16 v[114:117], v[174:177], v[192:195], v[114:117]
	v_mfma_f32_16x16x32_bf16 v[102:105], v[166:169], v[200:203], v[102:105]
	v_mfma_f32_16x16x32_bf16 v[98:101], v[174:177], v[200:203], v[98:101]
	v_mfma_f32_16x16x32_bf16 v[86:89], v[166:169], v[218:221], v[86:89]
	v_mfma_f32_16x16x32_bf16 v[82:85], v[174:177], v[218:221], v[82:85]
	v_mfma_f32_16x16x32_bf16 v[70:73], v[166:169], v[226:229], v[70:73]
	v_mfma_f32_16x16x32_bf16 v[66:69], v[174:177], v[226:229], v[66:69]
	s_setprio 0
	s_barrier
	s_add_i32 s42, s42, s2
	v_lshl_add_u64 v[160:161], s[18:19], 0, v[0:1]
	s_mov_b32 m0, s42
	ds_read_b128 v[188:191], v165 offset:16384
	ds_read_b128 v[192:195], v165 offset:17408
	ds_read_b128 v[196:199], v165 offset:18432
	ds_read_b128 v[200:203], v165 offset:19456
	ds_read_b128 v[204:207], v165 offset:20480
	ds_read_b128 v[218:221], v165 offset:21504
	ds_read_b128 v[222:225], v165 offset:22528
	ds_read_b128 v[226:229], v165 offset:23552
	global_load_lds_dwordx4 v[160:161], off
	s_add_i32 m0, s42, 0x2000
	s_add_u32 s44, s18, 0x80000
	v_lshl_add_u64 v[178:179], s[18:19], 0, v[130:131]
	s_addc_u32 s45, s19, 0
	s_add_i32 s3, s3, s2
	global_load_lds_dwordx4 v[178:179], off
	s_mov_b32 m0, s3
	v_lshl_add_u64 v[182:183], s[20:21], 0, v[132:133]
	global_load_lds_dwordx4 v0, s[44:45]
	s_add_i32 m0, s3, 0x2000
	s_nop 0
	global_load_lds_dwordx4 v130, s[44:45]
	v_lshl_add_u64 v[180:181], s[20:21], 0, v[134:135]
	s_mov_b32 m0, s22
	s_nop 0
	global_load_lds_dwordx4 v[180:181], off
	s_mov_b32 m0, s23
	s_nop 0
	global_load_lds_dwordx4 v[182:183], off
	s_waitcnt vmcnt(8)
	s_waitcnt lgkmcnt(0)
	s_waitcnt lgkmcnt(0)
	v_mfma_f32_16x16x32_bf16 v[62:65], v[140:143], v[188:191], v[62:65]
	v_mfma_f32_16x16x32_bf16 v[58:61], v[148:151], v[188:191], v[58:61]
	s_barrier
	s_setprio 1
	v_mfma_f32_16x16x32_bf16 v[46:49], v[140:143], v[196:199], v[46:49]
	v_mfma_f32_16x16x32_bf16 v[42:45], v[148:151], v[196:199], v[42:45]
	v_mfma_f32_16x16x32_bf16 v[30:33], v[140:143], v[204:207], v[30:33]
	v_mfma_f32_16x16x32_bf16 v[26:29], v[148:151], v[204:207], v[26:29]
	v_mfma_f32_16x16x32_bf16 v[14:17], v[140:143], v[222:225], v[14:17]
	v_mfma_f32_16x16x32_bf16 v[10:13], v[148:151], v[222:225], v[10:13]
	v_mfma_f32_16x16x32_bf16 v[62:65], v[144:147], v[192:195], v[62:65]
	v_mfma_f32_16x16x32_bf16 v[58:61], v[152:155], v[192:195], v[58:61]
	v_mfma_f32_16x16x32_bf16 v[46:49], v[144:147], v[200:203], v[46:49]
	v_mfma_f32_16x16x32_bf16 v[42:45], v[152:155], v[200:203], v[42:45]
	v_mfma_f32_16x16x32_bf16 v[30:33], v[144:147], v[218:221], v[30:33]
	v_mfma_f32_16x16x32_bf16 v[26:29], v[152:155], v[218:221], v[26:29]
	v_mfma_f32_16x16x32_bf16 v[14:17], v[144:147], v[226:229], v[14:17]
	v_mfma_f32_16x16x32_bf16 v[10:13], v[152:155], v[226:229], v[10:13]
	s_setprio 0
	s_setprio 1
	v_mfma_f32_16x16x32_bf16 v[54:57], v[156:159], v[188:191], v[54:57]
	v_mfma_f32_16x16x32_bf16 v[50:53], v[170:173], v[188:191], v[50:53]
	v_mfma_f32_16x16x32_bf16 v[38:41], v[156:159], v[196:199], v[38:41]
	v_mfma_f32_16x16x32_bf16 v[34:37], v[170:173], v[196:199], v[34:37]
	v_mfma_f32_16x16x32_bf16 v[22:25], v[156:159], v[204:207], v[22:25]
	v_mfma_f32_16x16x32_bf16 v[18:21], v[170:173], v[204:207], v[18:21]
	v_mfma_f32_16x16x32_bf16 v[6:9], v[156:159], v[222:225], v[6:9]
	v_mfma_f32_16x16x32_bf16 v[2:5], v[170:173], v[222:225], v[2:5]
	v_mfma_f32_16x16x32_bf16 v[54:57], v[166:169], v[192:195], v[54:57]
	v_mfma_f32_16x16x32_bf16 v[50:53], v[174:177], v[192:195], v[50:53]
	v_mfma_f32_16x16x32_bf16 v[38:41], v[166:169], v[200:203], v[38:41]
	v_mfma_f32_16x16x32_bf16 v[34:37], v[174:177], v[200:203], v[34:37]
	v_mfma_f32_16x16x32_bf16 v[22:25], v[166:169], v[218:221], v[22:25]
	v_mfma_f32_16x16x32_bf16 v[18:21], v[174:177], v[218:221], v[18:21]
	v_mfma_f32_16x16x32_bf16 v[6:9], v[166:169], v[226:229], v[6:9]
	v_mfma_f32_16x16x32_bf16 v[2:5], v[174:177], v[226:229], v[2:5]
	s_setprio 0
	s_barrier
	s_add_i32 s3, 0, 0x18000
	s_add_i32 s42, 0, 0x1c000
	v_add_u32_e32 v152, s3, v163
	v_add_u32_e32 v174, s42, v163
	ds_read_b128 v[140:143], v152
	ds_read_b128 v[144:147], v152 offset:1024
	ds_read_b128 v[148:151], v152 offset:2048
	ds_read_b128 v[152:155], v152 offset:3072
	ds_read_b128 v[156:159], v174
	ds_read_b128 v[166:169], v174 offset:1024
	ds_read_b128 v[170:173], v174 offset:2048
	ds_read_b128 v[174:177], v174 offset:3072
	s_add_u32 s20, s20, 0x80000
	s_addc_u32 s21, s21, 0
	s_mov_b32 m0, s24
	ds_read_b128 v[188:191], v165 offset:32768
	ds_read_b128 v[192:195], v165 offset:33792
	ds_read_b128 v[196:199], v165 offset:34816
	ds_read_b128 v[200:203], v165 offset:35840
	ds_read_b128 v[204:207], v165 offset:36864
	ds_read_b128 v[218:221], v165 offset:37888
	ds_read_b128 v[222:225], v165 offset:38912
	ds_read_b128 v[226:229], v165 offset:39936
	global_load_lds_dwordx4 v134, s[20:21]
	s_mov_b32 m0, s25
	s_nop 0
	global_load_lds_dwordx4 v132, s[20:21]
	s_waitcnt vmcnt(8)
	s_waitcnt lgkmcnt(0)
	s_waitcnt lgkmcnt(0)
	v_mfma_f32_16x16x32_bf16 v[126:129], v[140:143], v[188:191], v[126:129]
	v_mfma_f32_16x16x32_bf16 v[122:125], v[148:151], v[188:191], v[122:125]
	s_barrier
	s_setprio 1
	v_mfma_f32_16x16x32_bf16 v[110:113], v[140:143], v[196:199], v[110:113]
	v_mfma_f32_16x16x32_bf16 v[106:109], v[148:151], v[196:199], v[106:109]
	v_mfma_f32_16x16x32_bf16 v[94:97], v[140:143], v[204:207], v[94:97]
	v_mfma_f32_16x16x32_bf16 v[90:93], v[148:151], v[204:207], v[90:93]
	v_mfma_f32_16x16x32_bf16 v[78:81], v[140:143], v[222:225], v[78:81]
	v_mfma_f32_16x16x32_bf16 v[74:77], v[148:151], v[222:225], v[74:77]
	v_mfma_f32_16x16x32_bf16 v[126:129], v[144:147], v[192:195], v[126:129]
	v_mfma_f32_16x16x32_bf16 v[122:125], v[152:155], v[192:195], v[122:125]
	v_mfma_f32_16x16x32_bf16 v[110:113], v[144:147], v[200:203], v[110:113]
	v_mfma_f32_16x16x32_bf16 v[106:109], v[152:155], v[200:203], v[106:109]
	v_mfma_f32_16x16x32_bf16 v[94:97], v[144:147], v[218:221], v[94:97]
	v_mfma_f32_16x16x32_bf16 v[90:93], v[152:155], v[218:221], v[90:93]
	v_mfma_f32_16x16x32_bf16 v[78:81], v[144:147], v[226:229], v[78:81]
	v_mfma_f32_16x16x32_bf16 v[74:77], v[152:155], v[226:229], v[74:77]
	s_setprio 0
	s_setprio 1
	v_mfma_f32_16x16x32_bf16 v[118:121], v[156:159], v[188:191], v[118:121]
	v_mfma_f32_16x16x32_bf16 v[114:117], v[170:173], v[188:191], v[114:117]
	v_mfma_f32_16x16x32_bf16 v[102:105], v[156:159], v[196:199], v[102:105]
	v_mfma_f32_16x16x32_bf16 v[98:101], v[170:173], v[196:199], v[98:101]
	v_mfma_f32_16x16x32_bf16 v[86:89], v[156:159], v[204:207], v[86:89]
	v_mfma_f32_16x16x32_bf16 v[82:85], v[170:173], v[204:207], v[82:85]
	v_mfma_f32_16x16x32_bf16 v[70:73], v[156:159], v[222:225], v[70:73]
	v_mfma_f32_16x16x32_bf16 v[66:69], v[170:173], v[222:225], v[66:69]
	v_mfma_f32_16x16x32_bf16 v[118:121], v[166:169], v[192:195], v[118:121]
	v_mfma_f32_16x16x32_bf16 v[114:117], v[174:177], v[192:195], v[114:117]
	v_mfma_f32_16x16x32_bf16 v[102:105], v[166:169], v[200:203], v[102:105]
	v_mfma_f32_16x16x32_bf16 v[98:101], v[174:177], v[200:203], v[98:101]
	v_mfma_f32_16x16x32_bf16 v[86:89], v[166:169], v[218:221], v[86:89]
	v_mfma_f32_16x16x32_bf16 v[82:85], v[174:177], v[218:221], v[82:85]
	v_mfma_f32_16x16x32_bf16 v[70:73], v[166:169], v[226:229], v[70:73]
	v_mfma_f32_16x16x32_bf16 v[66:69], v[174:177], v[226:229], v[66:69]
	s_setprio 0
	s_barrier
	s_add_i32 s3, s3, s2
	v_lshl_add_u64 v[160:161], v[160:161], 0, s[52:53]
	s_mov_b32 m0, s3
	ds_read_b128 v[188:191], v165 offset:49152
	ds_read_b128 v[192:195], v165 offset:50176
	ds_read_b128 v[196:199], v165 offset:51200
	ds_read_b128 v[200:203], v165 offset:52224
	ds_read_b128 v[204:207], v165 offset:53248
	ds_read_b128 v[218:221], v165 offset:54272
	ds_read_b128 v[222:225], v165 offset:55296
	ds_read_b128 v[226:229], v165 offset:56320
	global_load_lds_dwordx4 v[160:161], off
	s_add_i32 m0, s3, 0x2000
	s_add_u32 s18, s18, 0x80080
	v_lshl_add_u64 v[160:161], v[178:179], 0, s[52:53]
	s_addc_u32 s19, s19, 0
	s_add_i32 s3, s42, s2
	global_load_lds_dwordx4 v[160:161], off
	s_mov_b32 m0, s3
	s_nop 0
	global_load_lds_dwordx4 v0, s[18:19]
	s_add_i32 m0, s3, 0x2000
	s_nop 0
	global_load_lds_dwordx4 v130, s[18:19]
	v_lshl_add_u64 v[160:161], v[180:181], 0, s[52:53]
	s_mov_b32 m0, s26
	s_nop 0
	global_load_lds_dwordx4 v[160:161], off
	v_lshl_add_u64 v[160:161], v[182:183], 0, s[52:53]
	s_mov_b32 m0, s27
	s_nop 0
	global_load_lds_dwordx4 v[160:161], off
	s_waitcnt vmcnt(8)
	s_waitcnt lgkmcnt(0)
	s_waitcnt lgkmcnt(0)
	v_mfma_f32_16x16x32_bf16 v[62:65], v[140:143], v[188:191], v[62:65]
	v_mfma_f32_16x16x32_bf16 v[58:61], v[148:151], v[188:191], v[58:61]
	s_barrier
	s_setprio 1
	v_mfma_f32_16x16x32_bf16 v[46:49], v[140:143], v[196:199], v[46:49]
	v_mfma_f32_16x16x32_bf16 v[42:45], v[148:151], v[196:199], v[42:45]
	v_mfma_f32_16x16x32_bf16 v[30:33], v[140:143], v[204:207], v[30:33]
	v_mfma_f32_16x16x32_bf16 v[26:29], v[148:151], v[204:207], v[26:29]
	v_mfma_f32_16x16x32_bf16 v[14:17], v[140:143], v[222:225], v[14:17]
	v_mfma_f32_16x16x32_bf16 v[10:13], v[148:151], v[222:225], v[10:13]
	v_mfma_f32_16x16x32_bf16 v[62:65], v[144:147], v[192:195], v[62:65]
	v_mfma_f32_16x16x32_bf16 v[58:61], v[152:155], v[192:195], v[58:61]
	v_mfma_f32_16x16x32_bf16 v[46:49], v[144:147], v[200:203], v[46:49]
	v_mfma_f32_16x16x32_bf16 v[42:45], v[152:155], v[200:203], v[42:45]
	v_mfma_f32_16x16x32_bf16 v[30:33], v[144:147], v[218:221], v[30:33]
	v_mfma_f32_16x16x32_bf16 v[26:29], v[152:155], v[218:221], v[26:29]
	v_mfma_f32_16x16x32_bf16 v[14:17], v[144:147], v[226:229], v[14:17]
	v_mfma_f32_16x16x32_bf16 v[10:13], v[152:155], v[226:229], v[10:13]
	s_setprio 0
	s_setprio 1
	v_mfma_f32_16x16x32_bf16 v[54:57], v[156:159], v[188:191], v[54:57]
	v_mfma_f32_16x16x32_bf16 v[50:53], v[170:173], v[188:191], v[50:53]
	v_mfma_f32_16x16x32_bf16 v[38:41], v[156:159], v[196:199], v[38:41]
	v_mfma_f32_16x16x32_bf16 v[34:37], v[170:173], v[196:199], v[34:37]
	v_mfma_f32_16x16x32_bf16 v[22:25], v[156:159], v[204:207], v[22:25]
	v_mfma_f32_16x16x32_bf16 v[18:21], v[170:173], v[204:207], v[18:21]
	v_mfma_f32_16x16x32_bf16 v[6:9], v[156:159], v[222:225], v[6:9]
	v_mfma_f32_16x16x32_bf16 v[2:5], v[170:173], v[222:225], v[2:5]
	v_mfma_f32_16x16x32_bf16 v[54:57], v[166:169], v[192:195], v[54:57]
	v_mfma_f32_16x16x32_bf16 v[50:53], v[174:177], v[192:195], v[50:53]
	v_mfma_f32_16x16x32_bf16 v[38:41], v[166:169], v[200:203], v[38:41]
	v_mfma_f32_16x16x32_bf16 v[34:37], v[174:177], v[200:203], v[34:37]
	v_mfma_f32_16x16x32_bf16 v[22:25], v[166:169], v[218:221], v[22:25]
	v_mfma_f32_16x16x32_bf16 v[18:21], v[174:177], v[218:221], v[18:21]
	v_mfma_f32_16x16x32_bf16 v[6:9], v[166:169], v[226:229], v[6:9]
	v_mfma_f32_16x16x32_bf16 v[2:5], v[174:177], v[226:229], v[2:5]
	s_setprio 0
	s_barrier
	s_add_i32 s41, s41, 2
	s_add_u32 s0, s0, 0x100
	s_addc_u32 s1, s1, 0
	s_add_u32 s35, s35, 0x100
	s_addc_u32 s40, s40, 0
	s_cmp_gt_u32 s41, 29
	s_cbranch_scc0 .LBB0_846
	s_and_b64 vcc, exec, s[8:9]
	s_movk_i32 s40, 0x4000
	s_movk_i32 s41, 0x6000
	s_cbranch_vccz .LBB0_849
	s_barrier

.LBB0_949:
	v_lshrrev_b32_e32 v18, 1, v8
	v_and_b32_e32 v18, 24, v18
	v_and_b32_e32 v9, 15, v8
	v_lshlrev_b32_e32 v19, 1, v18
	v_lshlrev_b32_e32 v8, 2, v8
	s_lshl_b32 s1, s1, 5
	v_lshl_or_b32 v142, s6, 6, v9
	v_lshl_or_b32 v9, v9, 6, v19
	s_lshl_b32 s3, s6, 13
	v_and_b32_e32 v8, 32, v8
	s_and_b32 s1, s1, 0x60
	v_lshl_add_u64 v[10:11], s[18:19], 0, v[0:1]
	v_mov_b32_e32 v131, v1
	v_readlane_b32 s16, v254, 38
	v_bitop3_b32 v19, v9, s3, v8 bitop3:0xde
	s_lshl_b32 s3, s1, 7
	v_lshl_add_u64 v[12:13], s[18:19], 0, v[130:131]
	v_mov_b32_e32 v135, v1
	v_readlane_b32 s17, v254, 39
	v_bitop3_b32 v143, v9, s3, v8 bitop3:0xde
	s_add_i32 m0, s25, 0x18000
	v_lshl_add_u64 v[8:9], v[10:11], 0, s[52:53]
	v_lshl_add_u64 v[14:15], s[16:17], 0, v[134:135]
	v_mov_b32_e32 v133, v1
	s_waitcnt vmcnt(2)
	s_barrier
	global_load_lds_dwordx4 v[8:9], off
	v_lshl_add_u64 v[8:9], v[12:13], 0, s[52:53]
	s_add_i32 m0, s25, 0x1a000
	s_add_i32 s29, s25, 0x8000
	s_add_i32 s30, s25, 0xa000
	v_lshl_add_u64 v[16:17], s[16:17], 0, v[132:133]
	global_load_lds_dwordx4 v[8:9], off
	v_lshl_add_u64 v[8:9], v[14:15], 0, s[52:53]
	s_mov_b32 m0, s29
	s_add_u32 s6, s18, 0x80080
	global_load_lds_dwordx4 v[8:9], off
	v_lshl_add_u64 v[8:9], v[16:17], 0, s[52:53]
	s_mov_b32 m0, s30
	s_addc_u32 s7, s19, 0
	global_load_lds_dwordx4 v[8:9], off
	s_add_i32 m0, s25, 0x1c000
	s_nop 0
	global_load_lds_dwordx4 v0, s[6:7]
	s_add_i32 m0, s25, 0x1e000
	s_cmpk_lt_u32 s0, 0x100
	global_load_lds_dwordx4 v130, s[6:7]
	v_lshlrev_b32_e32 v8, 15, v6
	v_and_b32_e32 v8, 0xffff0000, v8
	v_lshl_add_u32 v5, v5, 12, v8
	v_and_b32_e32 v6, 1, v6
	v_lshl_or_b32 v5, v6, 6, v5
	v_lshl_add_u32 v136, v7, 1, v5
	v_lshlrev_b32_e32 v5, 15, v2
	v_and_b32_e32 v5, 0xffff0000, v5
	s_waitcnt vmcnt(6)
	v_lshl_add_u32 v3, v3, 12, v5
	v_and_b32_e32 v2, 1, v2
	v_or_b32_e32 v144, s1, v18
	v_lshl_or_b32 v2, v2, 6, v3
	v_readlane_b32 s0, v254, 36
	s_cselect_b64 s[6:7], -1, 0
	v_mov_b32_e32 v137, v1
	v_lshl_add_u32 v138, v4, 1, v2
	v_mov_b32_e32 v139, v1
	s_mov_b32 s31, 0
	v_add_u32_e32 v145, 0, v19
	v_readlane_b32 s34, v254, 23
	s_mov_b32 s35, s0
	s_barrier
	v_readlane_b32 s1, v254, 37
	s_branch .LBB0_952

.LBB0_959:
	s_add_u32 s3, s16, 0xfff80080
	s_addc_u32 s18, s17, -1
	s_add_i32 s42, 0, 0x10000
	s_cmp_eq_u32 s46, 28
	s_cselect_b32 s21, s11, s18
	s_cselect_b32 s20, s40, s3
	v_add_u32_e32 v140, s42, v143
	s_cselect_b32 s19, s9, s45
	s_cselect_b32 s18, s41, s44
	s_add_i32 s3, 0, 0x14000
	ds_read_b128 v[146:149], v140
	ds_read_b128 v[150:153], v140 offset:1024
	ds_read_b128 v[154:157], v140 offset:2048
	ds_read_b128 v[158:161], v140 offset:3072
	v_add_u32_e32 v140, s3, v143
	ds_read_b128 v[162:165], v140
	ds_read_b128 v[166:169], v140 offset:1024
	ds_read_b128 v[170:173], v140 offset:2048
	ds_read_b128 v[174:177], v140 offset:3072
	s_add_i32 m0, s25, 0xc000
	ds_read_b128 v[188:191], v145
	ds_read_b128 v[192:195], v145 offset:1024
	ds_read_b128 v[196:199], v145 offset:2048
	ds_read_b128 v[200:203], v145 offset:3072
	ds_read_b128 v[204:207], v145 offset:4096
	ds_read_b128 v[218:221], v145 offset:5120
	ds_read_b128 v[222:225], v145 offset:6144
	ds_read_b128 v[226:229], v145 offset:7168
	global_load_lds_dwordx4 v136, s[16:17]
	s_add_i32 m0, s25, 0xe000
	s_nop 0
	global_load_lds_dwordx4 v138, s[16:17]
	s_waitcnt vmcnt(8)
	s_waitcnt lgkmcnt(0)
	s_waitcnt lgkmcnt(0)
	v_mfma_f32_16x16x32_bf16 v[126:129], v[146:149], v[188:191], v[126:129]
	v_mfma_f32_16x16x32_bf16 v[122:125], v[154:157], v[188:191], v[122:125]
	s_barrier
	s_setprio 1
	v_mfma_f32_16x16x32_bf16 v[110:113], v[146:149], v[196:199], v[110:113]
	v_mfma_f32_16x16x32_bf16 v[106:109], v[154:157], v[196:199], v[106:109]
	v_mfma_f32_16x16x32_bf16 v[94:97], v[146:149], v[204:207], v[94:97]
	v_mfma_f32_16x16x32_bf16 v[90:93], v[154:157], v[204:207], v[90:93]
	v_mfma_f32_16x16x32_bf16 v[78:81], v[146:149], v[222:225], v[78:81]
	v_mfma_f32_16x16x32_bf16 v[74:77], v[154:157], v[222:225], v[74:77]
	v_mfma_f32_16x16x32_bf16 v[126:129], v[150:153], v[192:195], v[126:129]
	v_mfma_f32_16x16x32_bf16 v[122:125], v[158:161], v[192:195], v[122:125]
	v_mfma_f32_16x16x32_bf16 v[110:113], v[150:153], v[200:203], v[110:113]
	v_mfma_f32_16x16x32_bf16 v[106:109], v[158:161], v[200:203], v[106:109]
	v_mfma_f32_16x16x32_bf16 v[94:97], v[150:153], v[218:221], v[94:97]
	v_mfma_f32_16x16x32_bf16 v[90:93], v[158:161], v[218:221], v[90:93]
	v_mfma_f32_16x16x32_bf16 v[78:81], v[150:153], v[226:229], v[78:81]
	v_mfma_f32_16x16x32_bf16 v[74:77], v[158:161], v[226:229], v[74:77]
	s_setprio 0
	s_setprio 1
	v_mfma_f32_16x16x32_bf16 v[118:121], v[162:165], v[188:191], v[118:121]
	v_mfma_f32_16x16x32_bf16 v[114:117], v[170:173], v[188:191], v[114:117]
	v_mfma_f32_16x16x32_bf16 v[102:105], v[162:165], v[196:199], v[102:105]
	v_mfma_f32_16x16x32_bf16 v[98:101], v[170:173], v[196:199], v[98:101]
	v_mfma_f32_16x16x32_bf16 v[86:89], v[162:165], v[204:207], v[86:89]
	v_mfma_f32_16x16x32_bf16 v[82:85], v[170:173], v[204:207], v[82:85]
	v_mfma_f32_16x16x32_bf16 v[70:73], v[162:165], v[222:225], v[70:73]
	v_mfma_f32_16x16x32_bf16 v[66:69], v[170:173], v[222:225], v[66:69]
	v_mfma_f32_16x16x32_bf16 v[118:121], v[166:169], v[192:195], v[118:121]
	v_mfma_f32_16x16x32_bf16 v[114:117], v[174:177], v[192:195], v[114:117]
	v_mfma_f32_16x16x32_bf16 v[102:105], v[166:169], v[200:203], v[102:105]
	v_mfma_f32_16x16x32_bf16 v[98:101], v[174:177], v[200:203], v[98:101]
	v_mfma_f32_16x16x32_bf16 v[86:89], v[166:169], v[218:221], v[86:89]
	v_mfma_f32_16x16x32_bf16 v[82:85], v[174:177], v[218:221], v[82:85]
	v_mfma_f32_16x16x32_bf16 v[70:73], v[166:169], v[226:229], v[70:73]
	v_mfma_f32_16x16x32_bf16 v[66:69], v[174:177], v[226:229], v[66:69]
	s_setprio 0
	s_barrier
	s_add_i32 s42, s42, s24
	v_lshl_add_u64 v[140:141], s[18:19], 0, v[0:1]
	s_mov_b32 m0, s42
	ds_read_b128 v[188:191], v145 offset:16384
	ds_read_b128 v[192:195], v145 offset:17408
	ds_read_b128 v[196:199], v145 offset:18432
	ds_read_b128 v[200:203], v145 offset:19456
	ds_read_b128 v[204:207], v145 offset:20480
	ds_read_b128 v[218:221], v145 offset:21504
	ds_read_b128 v[222:225], v145 offset:22528
	ds_read_b128 v[226:229], v145 offset:23552
	global_load_lds_dwordx4 v[140:141], off
	s_add_i32 m0, s42, 0x2000
	s_add_u32 s56, s18, 0x80000
	v_lshl_add_u64 v[178:179], s[18:19], 0, v[130:131]
	s_addc_u32 s57, s19, 0
	s_add_i32 s3, s3, s24
	global_load_lds_dwordx4 v[178:179], off
	s_mov_b32 m0, s3
	v_lshl_add_u64 v[182:183], s[20:21], 0, v[132:133]
	global_load_lds_dwordx4 v0, s[56:57]
	s_add_i32 m0, s3, 0x2000
	s_nop 0
	global_load_lds_dwordx4 v130, s[56:57]
	v_lshl_add_u64 v[180:181], s[20:21], 0, v[134:135]
	s_mov_b32 m0, s25
	s_nop 0
	global_load_lds_dwordx4 v[180:181], off
	s_mov_b32 m0, s26
	s_nop 0
	global_load_lds_dwordx4 v[182:183], off
	s_waitcnt vmcnt(8)
	s_waitcnt lgkmcnt(0)
	s_waitcnt lgkmcnt(0)
	v_mfma_f32_16x16x32_bf16 v[62:65], v[146:149], v[188:191], v[62:65]
	v_mfma_f32_16x16x32_bf16 v[58:61], v[154:157], v[188:191], v[58:61]
	s_barrier
	s_setprio 1
	v_mfma_f32_16x16x32_bf16 v[46:49], v[146:149], v[196:199], v[46:49]
	v_mfma_f32_16x16x32_bf16 v[42:45], v[154:157], v[196:199], v[42:45]
	v_mfma_f32_16x16x32_bf16 v[30:33], v[146:149], v[204:207], v[30:33]
	v_mfma_f32_16x16x32_bf16 v[26:29], v[154:157], v[204:207], v[26:29]
	v_mfma_f32_16x16x32_bf16 v[14:17], v[146:149], v[222:225], v[14:17]
	v_mfma_f32_16x16x32_bf16 v[10:13], v[154:157], v[222:225], v[10:13]
	v_mfma_f32_16x16x32_bf16 v[62:65], v[150:153], v[192:195], v[62:65]
	v_mfma_f32_16x16x32_bf16 v[58:61], v[158:161], v[192:195], v[58:61]
	v_mfma_f32_16x16x32_bf16 v[46:49], v[150:153], v[200:203], v[46:49]
	v_mfma_f32_16x16x32_bf16 v[42:45], v[158:161], v[200:203], v[42:45]
	v_mfma_f32_16x16x32_bf16 v[30:33], v[150:153], v[218:221], v[30:33]
	v_mfma_f32_16x16x32_bf16 v[26:29], v[158:161], v[218:221], v[26:29]
	v_mfma_f32_16x16x32_bf16 v[14:17], v[150:153], v[226:229], v[14:17]
	v_mfma_f32_16x16x32_bf16 v[10:13], v[158:161], v[226:229], v[10:13]
	s_setprio 0
	s_setprio 1
	v_mfma_f32_16x16x32_bf16 v[54:57], v[162:165], v[188:191], v[54:57]
	v_mfma_f32_16x16x32_bf16 v[50:53], v[170:173], v[188:191], v[50:53]
	v_mfma_f32_16x16x32_bf16 v[38:41], v[162:165], v[196:199], v[38:41]
	v_mfma_f32_16x16x32_bf16 v[34:37], v[170:173], v[196:199], v[34:37]
	v_mfma_f32_16x16x32_bf16 v[22:25], v[162:165], v[204:207], v[22:25]
	v_mfma_f32_16x16x32_bf16 v[18:21], v[170:173], v[204:207], v[18:21]
	v_mfma_f32_16x16x32_bf16 v[6:9], v[162:165], v[222:225], v[6:9]
	v_mfma_f32_16x16x32_bf16 v[2:5], v[170:173], v[222:225], v[2:5]
	v_mfma_f32_16x16x32_bf16 v[54:57], v[166:169], v[192:195], v[54:57]
	v_mfma_f32_16x16x32_bf16 v[50:53], v[174:177], v[192:195], v[50:53]
	v_mfma_f32_16x16x32_bf16 v[38:41], v[166:169], v[200:203], v[38:41]
	v_mfma_f32_16x16x32_bf16 v[34:37], v[174:177], v[200:203], v[34:37]
	v_mfma_f32_16x16x32_bf16 v[22:25], v[166:169], v[218:221], v[22:25]
	v_mfma_f32_16x16x32_bf16 v[18:21], v[174:177], v[218:221], v[18:21]
	v_mfma_f32_16x16x32_bf16 v[6:9], v[166:169], v[226:229], v[6:9]
	v_mfma_f32_16x16x32_bf16 v[2:5], v[174:177], v[226:229], v[2:5]
	s_setprio 0
	s_barrier
	s_add_i32 s3, 0, 0x18000
	s_add_i32 s42, 0, 0x1c000
	v_add_u32_e32 v158, s3, v143
	v_add_u32_e32 v174, s42, v143
	ds_read_b128 v[146:149], v158
	ds_read_b128 v[150:153], v158 offset:1024
	ds_read_b128 v[154:157], v158 offset:2048
	ds_read_b128 v[158:161], v158 offset:3072
	ds_read_b128 v[162:165], v174
	ds_read_b128 v[166:169], v174 offset:1024
	ds_read_b128 v[170:173], v174 offset:2048
	ds_read_b128 v[174:177], v174 offset:3072
	s_add_u32 s20, s20, 0x80000
	s_addc_u32 s21, s21, 0
	s_mov_b32 m0, s27
	ds_read_b128 v[188:191], v145 offset:32768
	ds_read_b128 v[192:195], v145 offset:33792
	ds_read_b128 v[196:199], v145 offset:34816
	ds_read_b128 v[200:203], v145 offset:35840
	ds_read_b128 v[204:207], v145 offset:36864
	ds_read_b128 v[218:221], v145 offset:37888
	ds_read_b128 v[222:225], v145 offset:38912
	ds_read_b128 v[226:229], v145 offset:39936
	global_load_lds_dwordx4 v134, s[20:21]
	s_mov_b32 m0, s28
	s_nop 0
	global_load_lds_dwordx4 v132, s[20:21]
	s_waitcnt vmcnt(8)
	s_waitcnt lgkmcnt(0)
	s_waitcnt lgkmcnt(0)
	v_mfma_f32_16x16x32_bf16 v[126:129], v[146:149], v[188:191], v[126:129]
	v_mfma_f32_16x16x32_bf16 v[122:125], v[154:157], v[188:191], v[122:125]
	s_barrier
	s_setprio 1
	v_mfma_f32_16x16x32_bf16 v[110:113], v[146:149], v[196:199], v[110:113]
	v_mfma_f32_16x16x32_bf16 v[106:109], v[154:157], v[196:199], v[106:109]
	v_mfma_f32_16x16x32_bf16 v[94:97], v[146:149], v[204:207], v[94:97]
	v_mfma_f32_16x16x32_bf16 v[90:93], v[154:157], v[204:207], v[90:93]
	v_mfma_f32_16x16x32_bf16 v[78:81], v[146:149], v[222:225], v[78:81]
	v_mfma_f32_16x16x32_bf16 v[74:77], v[154:157], v[222:225], v[74:77]
	v_mfma_f32_16x16x32_bf16 v[126:129], v[150:153], v[192:195], v[126:129]
	v_mfma_f32_16x16x32_bf16 v[122:125], v[158:161], v[192:195], v[122:125]
	v_mfma_f32_16x16x32_bf16 v[110:113], v[150:153], v[200:203], v[110:113]
	v_mfma_f32_16x16x32_bf16 v[106:109], v[158:161], v[200:203], v[106:109]
	v_mfma_f32_16x16x32_bf16 v[94:97], v[150:153], v[218:221], v[94:97]
	v_mfma_f32_16x16x32_bf16 v[90:93], v[158:161], v[218:221], v[90:93]
	v_mfma_f32_16x16x32_bf16 v[78:81], v[150:153], v[226:229], v[78:81]
	v_mfma_f32_16x16x32_bf16 v[74:77], v[158:161], v[226:229], v[74:77]
	s_setprio 0
	s_setprio 1
	v_mfma_f32_16x16x32_bf16 v[118:121], v[162:165], v[188:191], v[118:121]
	v_mfma_f32_16x16x32_bf16 v[114:117], v[170:173], v[188:191], v[114:117]
	v_mfma_f32_16x16x32_bf16 v[102:105], v[162:165], v[196:199], v[102:105]
	v_mfma_f32_16x16x32_bf16 v[98:101], v[170:173], v[196:199], v[98:101]
	v_mfma_f32_16x16x32_bf16 v[86:89], v[162:165], v[204:207], v[86:89]
	v_mfma_f32_16x16x32_bf16 v[82:85], v[170:173], v[204:207], v[82:85]
	v_mfma_f32_16x16x32_bf16 v[70:73], v[162:165], v[222:225], v[70:73]
	v_mfma_f32_16x16x32_bf16 v[66:69], v[170:173], v[222:225], v[66:69]
	v_mfma_f32_16x16x32_bf16 v[118:121], v[166:169], v[192:195], v[118:121]
	v_mfma_f32_16x16x32_bf16 v[114:117], v[174:177], v[192:195], v[114:117]
	v_mfma_f32_16x16x32_bf16 v[102:105], v[166:169], v[200:203], v[102:105]
	v_mfma_f32_16x16x32_bf16 v[98:101], v[174:177], v[200:203], v[98:101]
	v_mfma_f32_16x16x32_bf16 v[86:89], v[166:169], v[218:221], v[86:89]
	v_mfma_f32_16x16x32_bf16 v[82:85], v[174:177], v[218:221], v[82:85]
	v_mfma_f32_16x16x32_bf16 v[70:73], v[166:169], v[226:229], v[70:73]
	v_mfma_f32_16x16x32_bf16 v[66:69], v[174:177], v[226:229], v[66:69]
	s_setprio 0
	s_barrier
	s_add_i32 s3, s3, s24
	v_lshl_add_u64 v[140:141], v[140:141], 0, s[52:53]
	s_mov_b32 m0, s3
	ds_read_b128 v[188:191], v145 offset:49152
	ds_read_b128 v[192:195], v145 offset:50176
	ds_read_b128 v[196:199], v145 offset:51200
	ds_read_b128 v[200:203], v145 offset:52224
	ds_read_b128 v[204:207], v145 offset:53248
	ds_read_b128 v[218:221], v145 offset:54272
	ds_read_b128 v[222:225], v145 offset:55296
	ds_read_b128 v[226:229], v145 offset:56320
	global_load_lds_dwordx4 v[140:141], off
	s_add_i32 m0, s3, 0x2000
	s_add_u32 s18, s18, 0x80080
	v_lshl_add_u64 v[140:141], v[178:179], 0, s[52:53]
	s_addc_u32 s19, s19, 0
	s_add_i32 s3, s42, s24
	global_load_lds_dwordx4 v[140:141], off
	s_mov_b32 m0, s3
	s_nop 0
	global_load_lds_dwordx4 v0, s[18:19]
	s_add_i32 m0, s3, 0x2000
	s_nop 0
	global_load_lds_dwordx4 v130, s[18:19]
	v_lshl_add_u64 v[140:141], v[180:181], 0, s[52:53]
	s_mov_b32 m0, s29
	s_nop 0
	global_load_lds_dwordx4 v[140:141], off
	v_lshl_add_u64 v[140:141], v[182:183], 0, s[52:53]
	s_mov_b32 m0, s30
	s_nop 0
	global_load_lds_dwordx4 v[140:141], off
	s_waitcnt vmcnt(8)
	s_waitcnt lgkmcnt(0)
	s_waitcnt lgkmcnt(0)
	v_mfma_f32_16x16x32_bf16 v[62:65], v[146:149], v[188:191], v[62:65]
	v_mfma_f32_16x16x32_bf16 v[58:61], v[154:157], v[188:191], v[58:61]
	s_barrier
	s_setprio 1
	v_mfma_f32_16x16x32_bf16 v[46:49], v[146:149], v[196:199], v[46:49]
	v_mfma_f32_16x16x32_bf16 v[42:45], v[154:157], v[196:199], v[42:45]
	v_mfma_f32_16x16x32_bf16 v[30:33], v[146:149], v[204:207], v[30:33]
	v_mfma_f32_16x16x32_bf16 v[26:29], v[154:157], v[204:207], v[26:29]
	v_mfma_f32_16x16x32_bf16 v[14:17], v[146:149], v[222:225], v[14:17]
	v_mfma_f32_16x16x32_bf16 v[10:13], v[154:157], v[222:225], v[10:13]
	v_mfma_f32_16x16x32_bf16 v[62:65], v[150:153], v[192:195], v[62:65]
	v_mfma_f32_16x16x32_bf16 v[58:61], v[158:161], v[192:195], v[58:61]
	v_mfma_f32_16x16x32_bf16 v[46:49], v[150:153], v[200:203], v[46:49]
	v_mfma_f32_16x16x32_bf16 v[42:45], v[158:161], v[200:203], v[42:45]
	v_mfma_f32_16x16x32_bf16 v[30:33], v[150:153], v[218:221], v[30:33]
	v_mfma_f32_16x16x32_bf16 v[26:29], v[158:161], v[218:221], v[26:29]
	v_mfma_f32_16x16x32_bf16 v[14:17], v[150:153], v[226:229], v[14:17]
	v_mfma_f32_16x16x32_bf16 v[10:13], v[158:161], v[226:229], v[10:13]
	s_setprio 0
	s_setprio 1
	v_mfma_f32_16x16x32_bf16 v[54:57], v[162:165], v[188:191], v[54:57]
	v_mfma_f32_16x16x32_bf16 v[50:53], v[170:173], v[188:191], v[50:53]
	v_mfma_f32_16x16x32_bf16 v[38:41], v[162:165], v[196:199], v[38:41]
	v_mfma_f32_16x16x32_bf16 v[34:37], v[170:173], v[196:199], v[34:37]
	v_mfma_f32_16x16x32_bf16 v[22:25], v[162:165], v[204:207], v[22:25]
	v_mfma_f32_16x16x32_bf16 v[18:21], v[170:173], v[204:207], v[18:21]
	v_mfma_f32_16x16x32_bf16 v[6:9], v[162:165], v[222:225], v[6:9]
	v_mfma_f32_16x16x32_bf16 v[2:5], v[170:173], v[222:225], v[2:5]
	v_mfma_f32_16x16x32_bf16 v[54:57], v[166:169], v[192:195], v[54:57]
	v_mfma_f32_16x16x32_bf16 v[50:53], v[174:177], v[192:195], v[50:53]
	v_mfma_f32_16x16x32_bf16 v[38:41], v[166:169], v[200:203], v[38:41]
	v_mfma_f32_16x16x32_bf16 v[34:37], v[174:177], v[200:203], v[34:37]
	v_mfma_f32_16x16x32_bf16 v[22:25], v[166:169], v[218:221], v[22:25]
	v_mfma_f32_16x16x32_bf16 v[18:21], v[174:177], v[218:221], v[18:21]
	v_mfma_f32_16x16x32_bf16 v[6:9], v[166:169], v[226:229], v[6:9]
	v_mfma_f32_16x16x32_bf16 v[2:5], v[174:177], v[226:229], v[2:5]
	s_setprio 0
	s_barrier
	s_add_i32 s46, s46, 2
	s_add_u32 s16, s16, 0x100
	s_addc_u32 s17, s17, 0
	s_add_u32 s44, s44, 0x100
	s_addc_u32 s45, s45, 0
	s_cmp_gt_u32 s46, 29
	s_cbranch_scc0 .LBB0_959
	s_and_b64 vcc, exec, s[6:7]
	s_movk_i32 s40, 0x4000
	s_movk_i32 s41, 0x6000
	s_mov_b32 s44, 0x8000
	s_mov_b32 s45, 0xa000
	s_cbranch_vccz .LBB0_962
	s_barrier

.LBB0_1014:
	v_lshrrev_b32_e32 v18, 1, v8
	v_and_b32_e32 v18, 24, v18
	v_and_b32_e32 v9, 15, v8
	v_lshlrev_b32_e32 v19, 1, v18
	v_lshlrev_b32_e32 v8, 2, v8
	v_lshl_or_b32 v162, s10, 6, v9
	v_lshl_or_b32 v9, v9, 6, v19
	s_lshl_b32 s3, s10, 13
	v_and_b32_e32 v8, 32, v8
	v_bitop3_b32 v19, v9, s3, v8 bitop3:0xde
	s_lshl_b32 s3, s5, 5
	s_and_b32 s3, s3, 0x60
	v_lshl_add_u64 v[10:11], s[22:23], 0, v[0:1]
	v_mov_b32_e32 v131, v1
	v_readlane_b32 s20, v254, 50
	s_lshl_b32 s5, s3, 7
	v_lshl_add_u64 v[12:13], s[22:23], 0, v[130:131]
	v_mov_b32_e32 v135, v1
	v_readlane_b32 s21, v254, 51
	v_bitop3_b32 v163, v9, s5, v8 bitop3:0xde
	s_add_i32 m0, s28, 0x18000
	v_lshl_add_u64 v[8:9], v[10:11], 0, s[52:53]
	v_lshl_add_u64 v[14:15], s[20:21], 0, v[134:135]
	v_mov_b32_e32 v133, v1
	s_waitcnt vmcnt(2)
	s_barrier
	global_load_lds_dwordx4 v[8:9], off
	v_lshl_add_u64 v[8:9], v[12:13], 0, s[52:53]
	s_add_i32 m0, s28, 0x1a000
	s_add_i32 s34, s28, 0x8000
	s_add_i32 s35, s28, 0xa000
	v_lshl_add_u64 v[16:17], s[20:21], 0, v[132:133]
	global_load_lds_dwordx4 v[8:9], off
	v_lshl_add_u64 v[8:9], v[14:15], 0, s[52:53]
	s_mov_b32 m0, s34
	s_add_u32 s10, s22, 0x200080
	global_load_lds_dwordx4 v[8:9], off
	v_lshl_add_u64 v[8:9], v[16:17], 0, s[52:53]
	s_mov_b32 m0, s35
	s_addc_u32 s11, s23, 0
	global_load_lds_dwordx4 v[8:9], off
	s_add_i32 m0, s28, 0x1c000
	s_nop 0
	global_load_lds_dwordx4 v0, s[10:11]
	s_add_i32 m0, s28, 0x1e000
	s_cmpk_lt_u32 s4, 0x100
	global_load_lds_dwordx4 v130, s[10:11]
	v_lshlrev_b32_e32 v8, 17, v6
	v_and_b32_e32 v8, 0xfffc0000, v8
	v_lshl_add_u32 v5, v5, 14, v8
	v_and_b32_e32 v6, 1, v6
	v_lshl_or_b32 v5, v6, 6, v5
	v_lshl_add_u32 v136, v7, 1, v5
	v_lshlrev_b32_e32 v5, 17, v2
	v_and_b32_e32 v5, 0xfffc0000, v5
	s_waitcnt vmcnt(6)
	v_lshl_add_u32 v3, v3, 14, v5
	v_and_b32_e32 v2, 1, v2
	v_lshl_or_b32 v2, v2, 6, v3
	v_readlane_b32 s4, v254, 44
	s_cselect_b64 s[10:11], -1, 0
	v_or_b32_e32 v164, s3, v18
	v_mov_b32_e32 v137, v1
	v_lshl_add_u32 v138, v4, 1, v2
	v_mov_b32_e32 v139, v1
	s_mov_b32 s40, 0
	v_add_u32_e32 v165, 0, v19
	v_readlane_b32 s44, v254, 22
	s_mov_b32 s41, s4
	s_barrier
	v_readlane_b32 s5, v254, 45
	s_branch .LBB0_1017

.LBB0_1024:
	s_add_u32 s3, s20, 0xffe00080
	s_addc_u32 s22, s21, -1
	s_add_i32 s42, 0, 0x10000
	s_cmpk_eq_i32 s57, 0x7c
	s_cselect_b32 s25, s15, s22
	s_cselect_b32 s24, s45, s3
	s_cselect_b32 s23, s13, s56
	s_cselect_b32 s22, s46, s47
	s_add_i32 s3, 0, 0x14000
	v_add_u32_e32 v152, s42, v163
	v_add_u32_e32 v160, s3, v163
	ds_read_b128 v[140:143], v152
	ds_read_b128 v[144:147], v152 offset:1024
	ds_read_b128 v[148:151], v152 offset:2048
	ds_read_b128 v[152:155], v152 offset:3072
	ds_read_b128 v[156:159], v160
	ds_read_b128 v[166:169], v160 offset:1024
	ds_read_b128 v[170:173], v160 offset:2048
	ds_read_b128 v[174:177], v160 offset:3072
	s_add_i32 m0, s28, 0xc000
	ds_read_b128 v[188:191], v165
	ds_read_b128 v[192:195], v165 offset:1024
	ds_read_b128 v[196:199], v165 offset:2048
	ds_read_b128 v[200:203], v165 offset:3072
	ds_read_b128 v[204:207], v165 offset:4096
	ds_read_b128 v[218:221], v165 offset:5120
	ds_read_b128 v[222:225], v165 offset:6144
	ds_read_b128 v[226:229], v165 offset:7168
	global_load_lds_dwordx4 v136, s[20:21]
	s_add_i32 m0, s28, 0xe000
	s_nop 0
	global_load_lds_dwordx4 v138, s[20:21]
	s_waitcnt vmcnt(8)
	s_waitcnt lgkmcnt(0)
	s_waitcnt lgkmcnt(0)
	v_mfma_f32_16x16x32_bf16 v[126:129], v[140:143], v[188:191], v[126:129]
	v_mfma_f32_16x16x32_bf16 v[122:125], v[148:151], v[188:191], v[122:125]
	s_barrier
	s_setprio 1
	v_mfma_f32_16x16x32_bf16 v[110:113], v[140:143], v[196:199], v[110:113]
	v_mfma_f32_16x16x32_bf16 v[106:109], v[148:151], v[196:199], v[106:109]
	v_mfma_f32_16x16x32_bf16 v[94:97], v[140:143], v[204:207], v[94:97]
	v_mfma_f32_16x16x32_bf16 v[90:93], v[148:151], v[204:207], v[90:93]
	v_mfma_f32_16x16x32_bf16 v[78:81], v[140:143], v[222:225], v[78:81]
	v_mfma_f32_16x16x32_bf16 v[74:77], v[148:151], v[222:225], v[74:77]
	v_mfma_f32_16x16x32_bf16 v[126:129], v[144:147], v[192:195], v[126:129]
	v_mfma_f32_16x16x32_bf16 v[122:125], v[152:155], v[192:195], v[122:125]
	v_mfma_f32_16x16x32_bf16 v[110:113], v[144:147], v[200:203], v[110:113]
	v_mfma_f32_16x16x32_bf16 v[106:109], v[152:155], v[200:203], v[106:109]
	v_mfma_f32_16x16x32_bf16 v[94:97], v[144:147], v[218:221], v[94:97]
	v_mfma_f32_16x16x32_bf16 v[90:93], v[152:155], v[218:221], v[90:93]
	v_mfma_f32_16x16x32_bf16 v[78:81], v[144:147], v[226:229], v[78:81]
	v_mfma_f32_16x16x32_bf16 v[74:77], v[152:155], v[226:229], v[74:77]
	s_setprio 0
	s_setprio 1
	v_mfma_f32_16x16x32_bf16 v[118:121], v[156:159], v[188:191], v[118:121]
	v_mfma_f32_16x16x32_bf16 v[114:117], v[170:173], v[188:191], v[114:117]
	v_mfma_f32_16x16x32_bf16 v[102:105], v[156:159], v[196:199], v[102:105]
	v_mfma_f32_16x16x32_bf16 v[98:101], v[170:173], v[196:199], v[98:101]
	v_mfma_f32_16x16x32_bf16 v[86:89], v[156:159], v[204:207], v[86:89]
	v_mfma_f32_16x16x32_bf16 v[82:85], v[170:173], v[204:207], v[82:85]
	v_mfma_f32_16x16x32_bf16 v[70:73], v[156:159], v[222:225], v[70:73]
	v_mfma_f32_16x16x32_bf16 v[66:69], v[170:173], v[222:225], v[66:69]
	v_mfma_f32_16x16x32_bf16 v[118:121], v[166:169], v[192:195], v[118:121]
	v_mfma_f32_16x16x32_bf16 v[114:117], v[174:177], v[192:195], v[114:117]
	v_mfma_f32_16x16x32_bf16 v[102:105], v[166:169], v[200:203], v[102:105]
	v_mfma_f32_16x16x32_bf16 v[98:101], v[174:177], v[200:203], v[98:101]
	v_mfma_f32_16x16x32_bf16 v[86:89], v[166:169], v[218:221], v[86:89]
	v_mfma_f32_16x16x32_bf16 v[82:85], v[174:177], v[218:221], v[82:85]
	v_mfma_f32_16x16x32_bf16 v[70:73], v[166:169], v[226:229], v[70:73]
	v_mfma_f32_16x16x32_bf16 v[66:69], v[174:177], v[226:229], v[66:69]
	s_setprio 0
	s_barrier
	s_add_i32 s42, s42, s27
	v_lshl_add_u64 v[160:161], s[22:23], 0, v[0:1]
	s_mov_b32 m0, s42
	ds_read_b128 v[188:191], v165 offset:16384
	ds_read_b128 v[192:195], v165 offset:17408
	ds_read_b128 v[196:199], v165 offset:18432
	ds_read_b128 v[200:203], v165 offset:19456
	ds_read_b128 v[204:207], v165 offset:20480
	ds_read_b128 v[218:221], v165 offset:21504
	ds_read_b128 v[222:225], v165 offset:22528
	ds_read_b128 v[226:229], v165 offset:23552
	global_load_lds_dwordx4 v[160:161], off
	s_add_i32 m0, s42, 0x2000
	s_add_u32 s58, s22, 0x200000
	v_lshl_add_u64 v[178:179], s[22:23], 0, v[130:131]
	s_addc_u32 s59, s23, 0
	s_add_i32 s3, s3, s27
	global_load_lds_dwordx4 v[178:179], off
	s_mov_b32 m0, s3
	v_lshl_add_u64 v[182:183], s[24:25], 0, v[132:133]
	global_load_lds_dwordx4 v0, s[58:59]
	s_add_i32 m0, s3, 0x2000
	s_nop 0
	global_load_lds_dwordx4 v130, s[58:59]
	v_lshl_add_u64 v[180:181], s[24:25], 0, v[134:135]
	s_mov_b32 m0, s28
	s_nop 0
	global_load_lds_dwordx4 v[180:181], off
	s_mov_b32 m0, s29
	s_nop 0
	global_load_lds_dwordx4 v[182:183], off
	s_waitcnt vmcnt(8)
	s_waitcnt lgkmcnt(0)
	s_waitcnt lgkmcnt(0)
	v_mfma_f32_16x16x32_bf16 v[62:65], v[140:143], v[188:191], v[62:65]
	v_mfma_f32_16x16x32_bf16 v[58:61], v[148:151], v[188:191], v[58:61]
	s_barrier
	s_setprio 1
	v_mfma_f32_16x16x32_bf16 v[46:49], v[140:143], v[196:199], v[46:49]
	v_mfma_f32_16x16x32_bf16 v[42:45], v[148:151], v[196:199], v[42:45]
	v_mfma_f32_16x16x32_bf16 v[30:33], v[140:143], v[204:207], v[30:33]
	v_mfma_f32_16x16x32_bf16 v[26:29], v[148:151], v[204:207], v[26:29]
	v_mfma_f32_16x16x32_bf16 v[14:17], v[140:143], v[222:225], v[14:17]
	v_mfma_f32_16x16x32_bf16 v[10:13], v[148:151], v[222:225], v[10:13]
	v_mfma_f32_16x16x32_bf16 v[62:65], v[144:147], v[192:195], v[62:65]
	v_mfma_f32_16x16x32_bf16 v[58:61], v[152:155], v[192:195], v[58:61]
	v_mfma_f32_16x16x32_bf16 v[46:49], v[144:147], v[200:203], v[46:49]
	v_mfma_f32_16x16x32_bf16 v[42:45], v[152:155], v[200:203], v[42:45]
	v_mfma_f32_16x16x32_bf16 v[30:33], v[144:147], v[218:221], v[30:33]
	v_mfma_f32_16x16x32_bf16 v[26:29], v[152:155], v[218:221], v[26:29]
	v_mfma_f32_16x16x32_bf16 v[14:17], v[144:147], v[226:229], v[14:17]
	v_mfma_f32_16x16x32_bf16 v[10:13], v[152:155], v[226:229], v[10:13]
	s_setprio 0
	s_setprio 1
	v_mfma_f32_16x16x32_bf16 v[54:57], v[156:159], v[188:191], v[54:57]
	v_mfma_f32_16x16x32_bf16 v[50:53], v[170:173], v[188:191], v[50:53]
	v_mfma_f32_16x16x32_bf16 v[38:41], v[156:159], v[196:199], v[38:41]
	v_mfma_f32_16x16x32_bf16 v[34:37], v[170:173], v[196:199], v[34:37]
	v_mfma_f32_16x16x32_bf16 v[22:25], v[156:159], v[204:207], v[22:25]
	v_mfma_f32_16x16x32_bf16 v[18:21], v[170:173], v[204:207], v[18:21]
	v_mfma_f32_16x16x32_bf16 v[6:9], v[156:159], v[222:225], v[6:9]
	v_mfma_f32_16x16x32_bf16 v[2:5], v[170:173], v[222:225], v[2:5]
	v_mfma_f32_16x16x32_bf16 v[54:57], v[166:169], v[192:195], v[54:57]
	v_mfma_f32_16x16x32_bf16 v[50:53], v[174:177], v[192:195], v[50:53]
	v_mfma_f32_16x16x32_bf16 v[38:41], v[166:169], v[200:203], v[38:41]
	v_mfma_f32_16x16x32_bf16 v[34:37], v[174:177], v[200:203], v[34:37]
	v_mfma_f32_16x16x32_bf16 v[22:25], v[166:169], v[218:221], v[22:25]
	v_mfma_f32_16x16x32_bf16 v[18:21], v[174:177], v[218:221], v[18:21]
	v_mfma_f32_16x16x32_bf16 v[6:9], v[166:169], v[226:229], v[6:9]
	v_mfma_f32_16x16x32_bf16 v[2:5], v[174:177], v[226:229], v[2:5]
	s_setprio 0
	s_barrier
	s_add_i32 s3, 0, 0x18000
	s_add_i32 s42, 0, 0x1c000
	v_add_u32_e32 v152, s3, v163
	v_add_u32_e32 v174, s42, v163
	ds_read_b128 v[140:143], v152
	ds_read_b128 v[144:147], v152 offset:1024
	ds_read_b128 v[148:151], v152 offset:2048
	ds_read_b128 v[152:155], v152 offset:3072
	ds_read_b128 v[156:159], v174
	ds_read_b128 v[166:169], v174 offset:1024
	ds_read_b128 v[170:173], v174 offset:2048
	ds_read_b128 v[174:177], v174 offset:3072
	s_add_u32 s24, s24, 0x200000
	s_addc_u32 s25, s25, 0
	s_mov_b32 m0, s30
	ds_read_b128 v[188:191], v165 offset:32768
	ds_read_b128 v[192:195], v165 offset:33792
	ds_read_b128 v[196:199], v165 offset:34816
	ds_read_b128 v[200:203], v165 offset:35840
	ds_read_b128 v[204:207], v165 offset:36864
	ds_read_b128 v[218:221], v165 offset:37888
	ds_read_b128 v[222:225], v165 offset:38912
	ds_read_b128 v[226:229], v165 offset:39936
	global_load_lds_dwordx4 v134, s[24:25]
	s_mov_b32 m0, s31
	s_nop 0
	global_load_lds_dwordx4 v132, s[24:25]
	s_waitcnt vmcnt(8)
	s_waitcnt lgkmcnt(0)
	s_waitcnt lgkmcnt(0)
	v_mfma_f32_16x16x32_bf16 v[126:129], v[140:143], v[188:191], v[126:129]
	v_mfma_f32_16x16x32_bf16 v[122:125], v[148:151], v[188:191], v[122:125]
	s_barrier
	s_setprio 1
	v_mfma_f32_16x16x32_bf16 v[110:113], v[140:143], v[196:199], v[110:113]
	v_mfma_f32_16x16x32_bf16 v[106:109], v[148:151], v[196:199], v[106:109]
	v_mfma_f32_16x16x32_bf16 v[94:97], v[140:143], v[204:207], v[94:97]
	v_mfma_f32_16x16x32_bf16 v[90:93], v[148:151], v[204:207], v[90:93]
	v_mfma_f32_16x16x32_bf16 v[78:81], v[140:143], v[222:225], v[78:81]
	v_mfma_f32_16x16x32_bf16 v[74:77], v[148:151], v[222:225], v[74:77]
	v_mfma_f32_16x16x32_bf16 v[126:129], v[144:147], v[192:195], v[126:129]
	v_mfma_f32_16x16x32_bf16 v[122:125], v[152:155], v[192:195], v[122:125]
	v_mfma_f32_16x16x32_bf16 v[110:113], v[144:147], v[200:203], v[110:113]
	v_mfma_f32_16x16x32_bf16 v[106:109], v[152:155], v[200:203], v[106:109]
	v_mfma_f32_16x16x32_bf16 v[94:97], v[144:147], v[218:221], v[94:97]
	v_mfma_f32_16x16x32_bf16 v[90:93], v[152:155], v[218:221], v[90:93]
	v_mfma_f32_16x16x32_bf16 v[78:81], v[144:147], v[226:229], v[78:81]
	v_mfma_f32_16x16x32_bf16 v[74:77], v[152:155], v[226:229], v[74:77]
	s_setprio 0
	s_setprio 1
	v_mfma_f32_16x16x32_bf16 v[118:121], v[156:159], v[188:191], v[118:121]
	v_mfma_f32_16x16x32_bf16 v[114:117], v[170:173], v[188:191], v[114:117]
	v_mfma_f32_16x16x32_bf16 v[102:105], v[156:159], v[196:199], v[102:105]
	v_mfma_f32_16x16x32_bf16 v[98:101], v[170:173], v[196:199], v[98:101]
	v_mfma_f32_16x16x32_bf16 v[86:89], v[156:159], v[204:207], v[86:89]
	v_mfma_f32_16x16x32_bf16 v[82:85], v[170:173], v[204:207], v[82:85]
	v_mfma_f32_16x16x32_bf16 v[70:73], v[156:159], v[222:225], v[70:73]
	v_mfma_f32_16x16x32_bf16 v[66:69], v[170:173], v[222:225], v[66:69]
	v_mfma_f32_16x16x32_bf16 v[118:121], v[166:169], v[192:195], v[118:121]
	v_mfma_f32_16x16x32_bf16 v[114:117], v[174:177], v[192:195], v[114:117]
	v_mfma_f32_16x16x32_bf16 v[102:105], v[166:169], v[200:203], v[102:105]
	v_mfma_f32_16x16x32_bf16 v[98:101], v[174:177], v[200:203], v[98:101]
	v_mfma_f32_16x16x32_bf16 v[86:89], v[166:169], v[218:221], v[86:89]
	v_mfma_f32_16x16x32_bf16 v[82:85], v[174:177], v[218:221], v[82:85]
	v_mfma_f32_16x16x32_bf16 v[70:73], v[166:169], v[226:229], v[70:73]
	v_mfma_f32_16x16x32_bf16 v[66:69], v[174:177], v[226:229], v[66:69]
	s_setprio 0
	s_barrier
	s_add_i32 s3, s3, s27
	v_lshl_add_u64 v[160:161], v[160:161], 0, s[52:53]
	s_mov_b32 m0, s3
	ds_read_b128 v[188:191], v165 offset:49152
	ds_read_b128 v[192:195], v165 offset:50176
	ds_read_b128 v[196:199], v165 offset:51200
	ds_read_b128 v[200:203], v165 offset:52224
	ds_read_b128 v[204:207], v165 offset:53248
	ds_read_b128 v[218:221], v165 offset:54272
	ds_read_b128 v[222:225], v165 offset:55296
	ds_read_b128 v[226:229], v165 offset:56320
	global_load_lds_dwordx4 v[160:161], off
	s_add_i32 m0, s3, 0x2000
	s_add_u32 s22, s22, 0x200080
	v_lshl_add_u64 v[160:161], v[178:179], 0, s[52:53]
	s_addc_u32 s23, s23, 0
	s_add_i32 s3, s42, s27
	global_load_lds_dwordx4 v[160:161], off
	s_mov_b32 m0, s3
	s_nop 0
	global_load_lds_dwordx4 v0, s[22:23]
	s_add_i32 m0, s3, 0x2000
	s_nop 0
	global_load_lds_dwordx4 v130, s[22:23]
	v_lshl_add_u64 v[160:161], v[180:181], 0, s[52:53]
	s_mov_b32 m0, s34
	s_nop 0
	global_load_lds_dwordx4 v[160:161], off
	v_lshl_add_u64 v[160:161], v[182:183], 0, s[52:53]
	s_mov_b32 m0, s35
	s_nop 0
	global_load_lds_dwordx4 v[160:161], off
	s_waitcnt vmcnt(8)
	s_waitcnt lgkmcnt(0)
	s_waitcnt lgkmcnt(0)
	v_mfma_f32_16x16x32_bf16 v[62:65], v[140:143], v[188:191], v[62:65]
	v_mfma_f32_16x16x32_bf16 v[58:61], v[148:151], v[188:191], v[58:61]
	s_barrier
	s_setprio 1
	v_mfma_f32_16x16x32_bf16 v[46:49], v[140:143], v[196:199], v[46:49]
	v_mfma_f32_16x16x32_bf16 v[42:45], v[148:151], v[196:199], v[42:45]
	v_mfma_f32_16x16x32_bf16 v[30:33], v[140:143], v[204:207], v[30:33]
	v_mfma_f32_16x16x32_bf16 v[26:29], v[148:151], v[204:207], v[26:29]
	v_mfma_f32_16x16x32_bf16 v[14:17], v[140:143], v[222:225], v[14:17]
	v_mfma_f32_16x16x32_bf16 v[10:13], v[148:151], v[222:225], v[10:13]
	v_mfma_f32_16x16x32_bf16 v[62:65], v[144:147], v[192:195], v[62:65]
	v_mfma_f32_16x16x32_bf16 v[58:61], v[152:155], v[192:195], v[58:61]
	v_mfma_f32_16x16x32_bf16 v[46:49], v[144:147], v[200:203], v[46:49]
	v_mfma_f32_16x16x32_bf16 v[42:45], v[152:155], v[200:203], v[42:45]
	v_mfma_f32_16x16x32_bf16 v[30:33], v[144:147], v[218:221], v[30:33]
	v_mfma_f32_16x16x32_bf16 v[26:29], v[152:155], v[218:221], v[26:29]
	v_mfma_f32_16x16x32_bf16 v[14:17], v[144:147], v[226:229], v[14:17]
	v_mfma_f32_16x16x32_bf16 v[10:13], v[152:155], v[226:229], v[10:13]
	s_setprio 0
	s_setprio 1
	v_mfma_f32_16x16x32_bf16 v[54:57], v[156:159], v[188:191], v[54:57]
	v_mfma_f32_16x16x32_bf16 v[50:53], v[170:173], v[188:191], v[50:53]
	v_mfma_f32_16x16x32_bf16 v[38:41], v[156:159], v[196:199], v[38:41]
	v_mfma_f32_16x16x32_bf16 v[34:37], v[170:173], v[196:199], v[34:37]
	v_mfma_f32_16x16x32_bf16 v[22:25], v[156:159], v[204:207], v[22:25]
	v_mfma_f32_16x16x32_bf16 v[18:21], v[170:173], v[204:207], v[18:21]
	v_mfma_f32_16x16x32_bf16 v[6:9], v[156:159], v[222:225], v[6:9]
	v_mfma_f32_16x16x32_bf16 v[2:5], v[170:173], v[222:225], v[2:5]
	v_mfma_f32_16x16x32_bf16 v[54:57], v[166:169], v[192:195], v[54:57]
	v_mfma_f32_16x16x32_bf16 v[50:53], v[174:177], v[192:195], v[50:53]
	v_mfma_f32_16x16x32_bf16 v[38:41], v[166:169], v[200:203], v[38:41]
	v_mfma_f32_16x16x32_bf16 v[34:37], v[174:177], v[200:203], v[34:37]
	v_mfma_f32_16x16x32_bf16 v[22:25], v[166:169], v[218:221], v[22:25]
	v_mfma_f32_16x16x32_bf16 v[18:21], v[174:177], v[218:221], v[18:21]
	v_mfma_f32_16x16x32_bf16 v[6:9], v[166:169], v[226:229], v[6:9]
	v_mfma_f32_16x16x32_bf16 v[2:5], v[174:177], v[226:229], v[2:5]
	s_setprio 0
	s_barrier
	s_add_i32 s57, s57, 2
	s_add_u32 s20, s20, 0x100
	s_addc_u32 s21, s21, 0
	s_add_u32 s47, s47, 0x100
	s_addc_u32 s56, s56, 0
	s_cmpk_gt_u32 s57, 0x7d
	s_cbranch_scc0 .LBB0_1024
	s_and_b64 vcc, exec, s[10:11]
	s_mov_b32 s45, 0xa000
	s_cbranch_vccz .LBB0_1027
	s_barrier

.LBB0_1036:
	v_lshrrev_b32_e32 v18, 1, v8
	v_and_b32_e32 v18, 24, v18
	v_and_b32_e32 v9, 15, v8
	v_lshlrev_b32_e32 v19, 1, v18
	v_lshlrev_b32_e32 v8, 2, v8
	s_lshl_b32 s1, s1, 5
	v_lshl_or_b32 v162, s8, 6, v9
	v_lshl_or_b32 v9, v9, 6, v19
	s_lshl_b32 s3, s8, 13
	v_and_b32_e32 v8, 32, v8
	s_and_b32 s1, s1, 0x60
	v_lshl_add_u64 v[10:11], s[20:21], 0, v[0:1]
	v_mov_b32_e32 v131, v1
	v_readlane_b32 s18, v254, 50
	v_bitop3_b32 v19, v9, s3, v8 bitop3:0xde
	s_lshl_b32 s3, s1, 7
	v_lshl_add_u64 v[12:13], s[20:21], 0, v[130:131]
	v_mov_b32_e32 v135, v1
	v_readlane_b32 s19, v254, 51
	v_bitop3_b32 v163, v9, s3, v8 bitop3:0xde
	s_add_i32 m0, s25, 0x18000
	v_lshl_add_u64 v[8:9], v[10:11], 0, s[52:53]
	v_lshl_add_u64 v[14:15], s[18:19], 0, v[134:135]
	v_mov_b32_e32 v133, v1
	s_waitcnt vmcnt(2)
	s_barrier
	global_load_lds_dwordx4 v[8:9], off
	v_lshl_add_u64 v[8:9], v[12:13], 0, s[52:53]
	s_add_i32 m0, s25, 0x1a000
	s_add_i32 s30, s25, 0x8000
	s_add_i32 s31, s25, 0xa000
	v_lshl_add_u64 v[16:17], s[18:19], 0, v[132:133]
	global_load_lds_dwordx4 v[8:9], off
	v_lshl_add_u64 v[8:9], v[14:15], 0, s[52:53]
	s_mov_b32 m0, s30
	s_add_u32 s8, s20, 0x200080
	global_load_lds_dwordx4 v[8:9], off
	v_lshl_add_u64 v[8:9], v[16:17], 0, s[52:53]
	s_mov_b32 m0, s31
	s_addc_u32 s9, s21, 0
	global_load_lds_dwordx4 v[8:9], off
	s_add_i32 m0, s25, 0x1c000
	s_nop 0
	global_load_lds_dwordx4 v0, s[8:9]
	s_add_i32 m0, s25, 0x1e000
	s_cmpk_lt_u32 s0, 0x100
	global_load_lds_dwordx4 v130, s[8:9]
	v_lshlrev_b32_e32 v8, 17, v6
	v_and_b32_e32 v8, 0xfffc0000, v8
	v_lshl_add_u32 v5, v5, 14, v8
	v_and_b32_e32 v6, 1, v6
	v_lshl_or_b32 v5, v6, 6, v5
	v_lshl_add_u32 v136, v7, 1, v5
	v_lshlrev_b32_e32 v5, 17, v2
	v_and_b32_e32 v5, 0xfffc0000, v5
	s_waitcnt vmcnt(6)
	v_lshl_add_u32 v3, v3, 14, v5
	v_and_b32_e32 v2, 1, v2
	v_or_b32_e32 v164, s1, v18
	v_lshl_or_b32 v2, v2, 6, v3
	v_readlane_b32 s0, v254, 44
	s_cselect_b64 s[8:9], -1, 0
	v_mov_b32_e32 v137, v1
	v_lshl_add_u32 v138, v4, 1, v2
	v_mov_b32_e32 v139, v1
	s_mov_b32 s34, 0
	v_add_u32_e32 v165, 0, v19
	v_readlane_b32 s40, v254, 22
	s_mov_b32 s35, s0
	s_barrier
	v_readlane_b32 s1, v254, 45
	s_branch .LBB0_1039

.LBB0_1046:
	s_add_u32 s3, s18, 0xffe00080
	s_addc_u32 s20, s19, -1
	s_add_i32 s42, 0, 0x10000
	s_cmpk_eq_i32 s47, 0x7c
	s_cselect_b32 s23, s13, s20
	s_cselect_b32 s22, s41, s3
	s_cselect_b32 s21, s11, s46
	s_cselect_b32 s20, s44, s45
	s_add_i32 s3, 0, 0x14000
	v_add_u32_e32 v152, s42, v163
	v_add_u32_e32 v160, s3, v163
	ds_read_b128 v[140:143], v152
	ds_read_b128 v[144:147], v152 offset:1024
	ds_read_b128 v[148:151], v152 offset:2048
	ds_read_b128 v[152:155], v152 offset:3072
	ds_read_b128 v[156:159], v160
	ds_read_b128 v[166:169], v160 offset:1024
	ds_read_b128 v[170:173], v160 offset:2048
	ds_read_b128 v[174:177], v160 offset:3072
	s_add_i32 m0, s25, 0xc000
	ds_read_b128 v[188:191], v165
	ds_read_b128 v[192:195], v165 offset:1024
	ds_read_b128 v[196:199], v165 offset:2048
	ds_read_b128 v[200:203], v165 offset:3072
	ds_read_b128 v[204:207], v165 offset:4096
	ds_read_b128 v[218:221], v165 offset:5120
	ds_read_b128 v[222:225], v165 offset:6144
	ds_read_b128 v[226:229], v165 offset:7168
	global_load_lds_dwordx4 v136, s[18:19]
	s_add_i32 m0, s25, 0xe000
	s_nop 0
	global_load_lds_dwordx4 v138, s[18:19]
	s_waitcnt vmcnt(8)
	s_waitcnt lgkmcnt(0)
	s_waitcnt lgkmcnt(0)
	v_mfma_f32_16x16x32_bf16 v[126:129], v[140:143], v[188:191], v[126:129]
	v_mfma_f32_16x16x32_bf16 v[122:125], v[148:151], v[188:191], v[122:125]
	s_barrier
	s_setprio 1
	v_mfma_f32_16x16x32_bf16 v[110:113], v[140:143], v[196:199], v[110:113]
	v_mfma_f32_16x16x32_bf16 v[106:109], v[148:151], v[196:199], v[106:109]
	v_mfma_f32_16x16x32_bf16 v[94:97], v[140:143], v[204:207], v[94:97]
	v_mfma_f32_16x16x32_bf16 v[90:93], v[148:151], v[204:207], v[90:93]
	v_mfma_f32_16x16x32_bf16 v[78:81], v[140:143], v[222:225], v[78:81]
	v_mfma_f32_16x16x32_bf16 v[74:77], v[148:151], v[222:225], v[74:77]
	v_mfma_f32_16x16x32_bf16 v[126:129], v[144:147], v[192:195], v[126:129]
	v_mfma_f32_16x16x32_bf16 v[122:125], v[152:155], v[192:195], v[122:125]
	v_mfma_f32_16x16x32_bf16 v[110:113], v[144:147], v[200:203], v[110:113]
	v_mfma_f32_16x16x32_bf16 v[106:109], v[152:155], v[200:203], v[106:109]
	v_mfma_f32_16x16x32_bf16 v[94:97], v[144:147], v[218:221], v[94:97]
	v_mfma_f32_16x16x32_bf16 v[90:93], v[152:155], v[218:221], v[90:93]
	v_mfma_f32_16x16x32_bf16 v[78:81], v[144:147], v[226:229], v[78:81]
	v_mfma_f32_16x16x32_bf16 v[74:77], v[152:155], v[226:229], v[74:77]
	s_setprio 0
	s_setprio 1
	v_mfma_f32_16x16x32_bf16 v[118:121], v[156:159], v[188:191], v[118:121]
	v_mfma_f32_16x16x32_bf16 v[114:117], v[170:173], v[188:191], v[114:117]
	v_mfma_f32_16x16x32_bf16 v[102:105], v[156:159], v[196:199], v[102:105]
	v_mfma_f32_16x16x32_bf16 v[98:101], v[170:173], v[196:199], v[98:101]
	v_mfma_f32_16x16x32_bf16 v[86:89], v[156:159], v[204:207], v[86:89]
	v_mfma_f32_16x16x32_bf16 v[82:85], v[170:173], v[204:207], v[82:85]
	v_mfma_f32_16x16x32_bf16 v[70:73], v[156:159], v[222:225], v[70:73]
	v_mfma_f32_16x16x32_bf16 v[66:69], v[170:173], v[222:225], v[66:69]
	v_mfma_f32_16x16x32_bf16 v[118:121], v[166:169], v[192:195], v[118:121]
	v_mfma_f32_16x16x32_bf16 v[114:117], v[174:177], v[192:195], v[114:117]
	v_mfma_f32_16x16x32_bf16 v[102:105], v[166:169], v[200:203], v[102:105]
	v_mfma_f32_16x16x32_bf16 v[98:101], v[174:177], v[200:203], v[98:101]
	v_mfma_f32_16x16x32_bf16 v[86:89], v[166:169], v[218:221], v[86:89]
	v_mfma_f32_16x16x32_bf16 v[82:85], v[174:177], v[218:221], v[82:85]
	v_mfma_f32_16x16x32_bf16 v[70:73], v[166:169], v[226:229], v[70:73]
	v_mfma_f32_16x16x32_bf16 v[66:69], v[174:177], v[226:229], v[66:69]
	s_setprio 0
	s_barrier
	s_add_i32 s42, s42, s24
	v_lshl_add_u64 v[160:161], s[20:21], 0, v[0:1]
	s_mov_b32 m0, s42
	ds_read_b128 v[188:191], v165 offset:16384
	ds_read_b128 v[192:195], v165 offset:17408
	ds_read_b128 v[196:199], v165 offset:18432
	ds_read_b128 v[200:203], v165 offset:19456
	ds_read_b128 v[204:207], v165 offset:20480
	ds_read_b128 v[218:221], v165 offset:21504
	ds_read_b128 v[222:225], v165 offset:22528
	ds_read_b128 v[226:229], v165 offset:23552
	global_load_lds_dwordx4 v[160:161], off
	s_add_i32 m0, s42, 0x2000
	s_add_u32 s56, s20, 0x200000
	v_lshl_add_u64 v[178:179], s[20:21], 0, v[130:131]
	s_addc_u32 s57, s21, 0
	s_add_i32 s3, s3, s24
	global_load_lds_dwordx4 v[178:179], off
	s_mov_b32 m0, s3
	v_lshl_add_u64 v[182:183], s[22:23], 0, v[132:133]
	global_load_lds_dwordx4 v0, s[56:57]
	s_add_i32 m0, s3, 0x2000
	s_nop 0
	global_load_lds_dwordx4 v130, s[56:57]
	v_lshl_add_u64 v[180:181], s[22:23], 0, v[134:135]
	s_mov_b32 m0, s25
	s_nop 0
	global_load_lds_dwordx4 v[180:181], off
	s_mov_b32 m0, s27
	s_nop 0
	global_load_lds_dwordx4 v[182:183], off
	s_waitcnt vmcnt(8)
	s_waitcnt lgkmcnt(0)
	s_waitcnt lgkmcnt(0)
	v_mfma_f32_16x16x32_bf16 v[62:65], v[140:143], v[188:191], v[62:65]
	v_mfma_f32_16x16x32_bf16 v[58:61], v[148:151], v[188:191], v[58:61]
	s_barrier
	s_setprio 1
	v_mfma_f32_16x16x32_bf16 v[46:49], v[140:143], v[196:199], v[46:49]
	v_mfma_f32_16x16x32_bf16 v[42:45], v[148:151], v[196:199], v[42:45]
	v_mfma_f32_16x16x32_bf16 v[30:33], v[140:143], v[204:207], v[30:33]
	v_mfma_f32_16x16x32_bf16 v[26:29], v[148:151], v[204:207], v[26:29]
	v_mfma_f32_16x16x32_bf16 v[14:17], v[140:143], v[222:225], v[14:17]
	v_mfma_f32_16x16x32_bf16 v[10:13], v[148:151], v[222:225], v[10:13]
	v_mfma_f32_16x16x32_bf16 v[62:65], v[144:147], v[192:195], v[62:65]
	v_mfma_f32_16x16x32_bf16 v[58:61], v[152:155], v[192:195], v[58:61]
	v_mfma_f32_16x16x32_bf16 v[46:49], v[144:147], v[200:203], v[46:49]
	v_mfma_f32_16x16x32_bf16 v[42:45], v[152:155], v[200:203], v[42:45]
	v_mfma_f32_16x16x32_bf16 v[30:33], v[144:147], v[218:221], v[30:33]
	v_mfma_f32_16x16x32_bf16 v[26:29], v[152:155], v[218:221], v[26:29]
	v_mfma_f32_16x16x32_bf16 v[14:17], v[144:147], v[226:229], v[14:17]
	v_mfma_f32_16x16x32_bf16 v[10:13], v[152:155], v[226:229], v[10:13]
	s_setprio 0
	s_setprio 1
	v_mfma_f32_16x16x32_bf16 v[54:57], v[156:159], v[188:191], v[54:57]
	v_mfma_f32_16x16x32_bf16 v[50:53], v[170:173], v[188:191], v[50:53]
	v_mfma_f32_16x16x32_bf16 v[38:41], v[156:159], v[196:199], v[38:41]
	v_mfma_f32_16x16x32_bf16 v[34:37], v[170:173], v[196:199], v[34:37]
	v_mfma_f32_16x16x32_bf16 v[22:25], v[156:159], v[204:207], v[22:25]
	v_mfma_f32_16x16x32_bf16 v[18:21], v[170:173], v[204:207], v[18:21]
	v_mfma_f32_16x16x32_bf16 v[6:9], v[156:159], v[222:225], v[6:9]
	v_mfma_f32_16x16x32_bf16 v[2:5], v[170:173], v[222:225], v[2:5]
	v_mfma_f32_16x16x32_bf16 v[54:57], v[166:169], v[192:195], v[54:57]
	v_mfma_f32_16x16x32_bf16 v[50:53], v[174:177], v[192:195], v[50:53]
	v_mfma_f32_16x16x32_bf16 v[38:41], v[166:169], v[200:203], v[38:41]
	v_mfma_f32_16x16x32_bf16 v[34:37], v[174:177], v[200:203], v[34:37]
	v_mfma_f32_16x16x32_bf16 v[22:25], v[166:169], v[218:221], v[22:25]
	v_mfma_f32_16x16x32_bf16 v[18:21], v[174:177], v[218:221], v[18:21]
	v_mfma_f32_16x16x32_bf16 v[6:9], v[166:169], v[226:229], v[6:9]
	v_mfma_f32_16x16x32_bf16 v[2:5], v[174:177], v[226:229], v[2:5]
	s_setprio 0
	s_barrier
	s_add_i32 s3, 0, 0x18000
	s_add_i32 s42, 0, 0x1c000
	v_add_u32_e32 v152, s3, v163
	v_add_u32_e32 v174, s42, v163
	ds_read_b128 v[140:143], v152
	ds_read_b128 v[144:147], v152 offset:1024
	ds_read_b128 v[148:151], v152 offset:2048
	ds_read_b128 v[152:155], v152 offset:3072
	ds_read_b128 v[156:159], v174
	ds_read_b128 v[166:169], v174 offset:1024
	ds_read_b128 v[170:173], v174 offset:2048
	ds_read_b128 v[174:177], v174 offset:3072
	s_add_u32 s22, s22, 0x200000
	s_addc_u32 s23, s23, 0
	s_mov_b32 m0, s28
	ds_read_b128 v[188:191], v165 offset:32768
	ds_read_b128 v[192:195], v165 offset:33792
	ds_read_b128 v[196:199], v165 offset:34816
	ds_read_b128 v[200:203], v165 offset:35840
	ds_read_b128 v[204:207], v165 offset:36864
	ds_read_b128 v[218:221], v165 offset:37888
	ds_read_b128 v[222:225], v165 offset:38912
	ds_read_b128 v[226:229], v165 offset:39936
	global_load_lds_dwordx4 v134, s[22:23]
	s_mov_b32 m0, s29
	s_nop 0
	global_load_lds_dwordx4 v132, s[22:23]
	s_waitcnt vmcnt(8)
	s_waitcnt lgkmcnt(0)
	s_waitcnt lgkmcnt(0)
	v_mfma_f32_16x16x32_bf16 v[126:129], v[140:143], v[188:191], v[126:129]
	v_mfma_f32_16x16x32_bf16 v[122:125], v[148:151], v[188:191], v[122:125]
	s_barrier
	s_setprio 1
	v_mfma_f32_16x16x32_bf16 v[110:113], v[140:143], v[196:199], v[110:113]
	v_mfma_f32_16x16x32_bf16 v[106:109], v[148:151], v[196:199], v[106:109]
	v_mfma_f32_16x16x32_bf16 v[94:97], v[140:143], v[204:207], v[94:97]
	v_mfma_f32_16x16x32_bf16 v[90:93], v[148:151], v[204:207], v[90:93]
	v_mfma_f32_16x16x32_bf16 v[78:81], v[140:143], v[222:225], v[78:81]
	v_mfma_f32_16x16x32_bf16 v[74:77], v[148:151], v[222:225], v[74:77]
	v_mfma_f32_16x16x32_bf16 v[126:129], v[144:147], v[192:195], v[126:129]
	v_mfma_f32_16x16x32_bf16 v[122:125], v[152:155], v[192:195], v[122:125]
	v_mfma_f32_16x16x32_bf16 v[110:113], v[144:147], v[200:203], v[110:113]
	v_mfma_f32_16x16x32_bf16 v[106:109], v[152:155], v[200:203], v[106:109]
	v_mfma_f32_16x16x32_bf16 v[94:97], v[144:147], v[218:221], v[94:97]
	v_mfma_f32_16x16x32_bf16 v[90:93], v[152:155], v[218:221], v[90:93]
	v_mfma_f32_16x16x32_bf16 v[78:81], v[144:147], v[226:229], v[78:81]
	v_mfma_f32_16x16x32_bf16 v[74:77], v[152:155], v[226:229], v[74:77]
	s_setprio 0
	s_setprio 1
	v_mfma_f32_16x16x32_bf16 v[118:121], v[156:159], v[188:191], v[118:121]
	v_mfma_f32_16x16x32_bf16 v[114:117], v[170:173], v[188:191], v[114:117]
	v_mfma_f32_16x16x32_bf16 v[102:105], v[156:159], v[196:199], v[102:105]
	v_mfma_f32_16x16x32_bf16 v[98:101], v[170:173], v[196:199], v[98:101]
	v_mfma_f32_16x16x32_bf16 v[86:89], v[156:159], v[204:207], v[86:89]
	v_mfma_f32_16x16x32_bf16 v[82:85], v[170:173], v[204:207], v[82:85]
	v_mfma_f32_16x16x32_bf16 v[70:73], v[156:159], v[222:225], v[70:73]
	v_mfma_f32_16x16x32_bf16 v[66:69], v[170:173], v[222:225], v[66:69]
	v_mfma_f32_16x16x32_bf16 v[118:121], v[166:169], v[192:195], v[118:121]
	v_mfma_f32_16x16x32_bf16 v[114:117], v[174:177], v[192:195], v[114:117]
	v_mfma_f32_16x16x32_bf16 v[102:105], v[166:169], v[200:203], v[102:105]
	v_mfma_f32_16x16x32_bf16 v[98:101], v[174:177], v[200:203], v[98:101]
	v_mfma_f32_16x16x32_bf16 v[86:89], v[166:169], v[218:221], v[86:89]
	v_mfma_f32_16x16x32_bf16 v[82:85], v[174:177], v[218:221], v[82:85]
	v_mfma_f32_16x16x32_bf16 v[70:73], v[166:169], v[226:229], v[70:73]
	v_mfma_f32_16x16x32_bf16 v[66:69], v[174:177], v[226:229], v[66:69]
	s_setprio 0
	s_barrier
	s_add_i32 s3, s3, s24
	v_lshl_add_u64 v[160:161], v[160:161], 0, s[52:53]
	s_mov_b32 m0, s3
	ds_read_b128 v[188:191], v165 offset:49152
	ds_read_b128 v[192:195], v165 offset:50176
	ds_read_b128 v[196:199], v165 offset:51200
	ds_read_b128 v[200:203], v165 offset:52224
	ds_read_b128 v[204:207], v165 offset:53248
	ds_read_b128 v[218:221], v165 offset:54272
	ds_read_b128 v[222:225], v165 offset:55296
	ds_read_b128 v[226:229], v165 offset:56320
	global_load_lds_dwordx4 v[160:161], off
	s_add_i32 m0, s3, 0x2000
	s_add_u32 s20, s20, 0x200080
	v_lshl_add_u64 v[160:161], v[178:179], 0, s[52:53]
	s_addc_u32 s21, s21, 0
	s_add_i32 s3, s42, s24
	global_load_lds_dwordx4 v[160:161], off
	s_mov_b32 m0, s3
	s_nop 0
	global_load_lds_dwordx4 v0, s[20:21]
	s_add_i32 m0, s3, 0x2000
	s_nop 0
	global_load_lds_dwordx4 v130, s[20:21]
	v_lshl_add_u64 v[160:161], v[180:181], 0, s[52:53]
	s_mov_b32 m0, s30
	s_nop 0
	global_load_lds_dwordx4 v[160:161], off
	v_lshl_add_u64 v[160:161], v[182:183], 0, s[52:53]
	s_mov_b32 m0, s31
	s_nop 0
	global_load_lds_dwordx4 v[160:161], off
	s_waitcnt vmcnt(8)
	s_waitcnt lgkmcnt(0)
	s_waitcnt lgkmcnt(0)
	v_mfma_f32_16x16x32_bf16 v[62:65], v[140:143], v[188:191], v[62:65]
	v_mfma_f32_16x16x32_bf16 v[58:61], v[148:151], v[188:191], v[58:61]
	s_barrier
	s_setprio 1
	v_mfma_f32_16x16x32_bf16 v[46:49], v[140:143], v[196:199], v[46:49]
	v_mfma_f32_16x16x32_bf16 v[42:45], v[148:151], v[196:199], v[42:45]
	v_mfma_f32_16x16x32_bf16 v[30:33], v[140:143], v[204:207], v[30:33]
	v_mfma_f32_16x16x32_bf16 v[26:29], v[148:151], v[204:207], v[26:29]
	v_mfma_f32_16x16x32_bf16 v[14:17], v[140:143], v[222:225], v[14:17]
	v_mfma_f32_16x16x32_bf16 v[10:13], v[148:151], v[222:225], v[10:13]
	v_mfma_f32_16x16x32_bf16 v[62:65], v[144:147], v[192:195], v[62:65]
	v_mfma_f32_16x16x32_bf16 v[58:61], v[152:155], v[192:195], v[58:61]
	v_mfma_f32_16x16x32_bf16 v[46:49], v[144:147], v[200:203], v[46:49]
	v_mfma_f32_16x16x32_bf16 v[42:45], v[152:155], v[200:203], v[42:45]
	v_mfma_f32_16x16x32_bf16 v[30:33], v[144:147], v[218:221], v[30:33]
	v_mfma_f32_16x16x32_bf16 v[26:29], v[152:155], v[218:221], v[26:29]
	v_mfma_f32_16x16x32_bf16 v[14:17], v[144:147], v[226:229], v[14:17]
	v_mfma_f32_16x16x32_bf16 v[10:13], v[152:155], v[226:229], v[10:13]
	s_setprio 0
	s_setprio 1
	v_mfma_f32_16x16x32_bf16 v[54:57], v[156:159], v[188:191], v[54:57]
	v_mfma_f32_16x16x32_bf16 v[50:53], v[170:173], v[188:191], v[50:53]
	v_mfma_f32_16x16x32_bf16 v[38:41], v[156:159], v[196:199], v[38:41]
	v_mfma_f32_16x16x32_bf16 v[34:37], v[170:173], v[196:199], v[34:37]
	v_mfma_f32_16x16x32_bf16 v[22:25], v[156:159], v[204:207], v[22:25]
	v_mfma_f32_16x16x32_bf16 v[18:21], v[170:173], v[204:207], v[18:21]
	v_mfma_f32_16x16x32_bf16 v[6:9], v[156:159], v[222:225], v[6:9]
	v_mfma_f32_16x16x32_bf16 v[2:5], v[170:173], v[222:225], v[2:5]
	v_mfma_f32_16x16x32_bf16 v[54:57], v[166:169], v[192:195], v[54:57]
	v_mfma_f32_16x16x32_bf16 v[50:53], v[174:177], v[192:195], v[50:53]
	v_mfma_f32_16x16x32_bf16 v[38:41], v[166:169], v[200:203], v[38:41]
	v_mfma_f32_16x16x32_bf16 v[34:37], v[174:177], v[200:203], v[34:37]
	v_mfma_f32_16x16x32_bf16 v[22:25], v[166:169], v[218:221], v[22:25]
	v_mfma_f32_16x16x32_bf16 v[18:21], v[174:177], v[218:221], v[18:21]
	v_mfma_f32_16x16x32_bf16 v[6:9], v[166:169], v[226:229], v[6:9]
	v_mfma_f32_16x16x32_bf16 v[2:5], v[174:177], v[226:229], v[2:5]
	s_setprio 0
	s_barrier
	s_add_i32 s47, s47, 2
	s_add_u32 s18, s18, 0x100
	s_addc_u32 s19, s19, 0
	s_add_u32 s45, s45, 0x100
	s_addc_u32 s46, s46, 0
	s_cmpk_gt_u32 s47, 0x7d
	s_cbranch_scc0 .LBB0_1046
	s_and_b64 vcc, exec, s[8:9]
	s_movk_i32 s41, 0x6000
	s_mov_b32 s44, 0x8000
	s_mov_b32 s45, 0xa000
	s_cbranch_vccz .LBB0_1049
	s_barrier
